# v27 + prep phase: half the workgroups run fold/WGT/SSM-table/XB sections before the weight transposes (overlap of ALU-bound and HBM-bound work), SGPR state snapshot/restore around the second pass
# baseline (speedup 1.0000x reference)
; #define LAS __attribute__((address_space(3)))
; __device__ __forceinline__ unsigned xb_ld(unsigned* p)              { return __hip_atomic_load(p, __ATOMIC_RELAXED, __HIP_MEMORY_SCOPE_AGENT); }
; __device__ __forceinline__ unsigned xb_add(unsigned* p, unsigned v) { return __hip_atomic_fetch_add(p, v, __ATOMIC_RELAXED, __HIP_MEMORY_SCOPE_AGENT); }
; __device__ __forceinline__ unsigned xb_xcc_id() { return (unsigned)__builtin_amdgcn_s_getreg((3 << 11) | 20) & 0xFu; }
; __device__ __forceinline__ XcdBarrier xcd_barrier_post(unsigned* bar, volatile LAS unsigned* st) {
;     XcdBarrier b; b.bar = bar; b.x = xb_xcc_id(); b.st = st;
;     if (threadIdx.x == 0) (void)xb_add(&bar[XB_XCNT(b.x)], 1u);
;     return b;
; }
; __device__ __forceinline__ void xcd_barrier_complete(unsigned* bar, unsigned x, unsigned& nloc, unsigned& nx) {
;     const unsigned G = gridDim.x * gridDim.y * gridDim.z;
;     unsigned sum, cnt, mine, sp = 0u;
;     for (;;) {
;         sum = 0u; cnt = 0u; mine = 0u;
; #pragma unroll
;         for (unsigned j = 0; j < 16; ++j) { const unsigned c = xb_ld(&bar[XB_XCNT(j)]); sum += c; cnt += (c > 0u) ? 1u : 0u; mine = (j == x) ? c : mine; }
;         if (sum == G) break;
;         __builtin_amdgcn_s_sleep(1);
;         if ((++sp & 255u) == 0u) { if (xb_ld(&bar[XB_TMO])) break; if (sp > XB_SPIN_CAP) { atomicAdd(&bar[XB_TMO], 1u); break; } }
;     }
;     nloc = mine > 0u ? mine : 1u; nx = cnt > 0u ? cnt : 1u;
; }
; __global__ void __launch_bounds__(512, 2) mega_fwd(Args a) {
;     ...
;     constexpr int G = 256;
;     unsigned char* ws = a.ws;
;     LAS unsigned char* ldsl = (LAS unsigned char*)lds;
;     unsigned long long* rssb = (unsigned long long*)(ws + WS_RSS);
;     volatile LAS unsigned* bst = (volatile LAS unsigned*)(ldsl + (LDS_BYTES - 64));
;     if (threadIdx.x < 2) bst[threadIdx.x] = 0u;
;     __syncthreads();
;     XcdBarrier bar = xcd_barrier_post((unsigned*)(ws + WS_BAR), bst);
.LBB0_18:
	s_add_u32 s4, s82, 0xe0200
	s_addc_u32 s5, s83, 0
	v_writelane_b32 v249, s4, 8
	s_mov_b32 s89, 0
	s_load_dwordx16 s[44:59], s[0:1], 0x0
	v_writelane_b32 v249, s5, 9
	s_add_u32 s4, s82, 0xe0400
	s_addc_u32 s5, s83, 0
	v_writelane_b32 v249, s4, 10
	v_mov_b32_e32 v137, 0
	v_mbcnt_lo_u32_b32 v0, -1, 0
	v_writelane_b32 v249, s5, 11
	s_add_u32 s4, s82, 0xe0500
	s_addc_u32 s5, s83, 0
	v_writelane_b32 v249, s4, 12
	v_mov_b32_e32 v175, 1
	v_mov_b32_e32 v176, 0x358637bd
	v_writelane_b32 v249, s5, 13
	s_add_u32 s4, s82, 0xe0600
	s_addc_u32 s5, s83, 0
	v_writelane_b32 v249, s4, 14
	v_mov_b64_e32 v[138:139], 0x200
	v_mov_b64_e32 v[140:141], 0x1ff
	v_writelane_b32 v249, s5, 15
	s_add_u32 s4, s82, 0xe0700
	s_addc_u32 s5, s83, 0
	v_writelane_b32 v249, s4, 16
	v_mbcnt_hi_u32_b32 v177, -1, v0
	v_mov_b64_e32 v[142:143], 0x80
	v_writelane_b32 v249, s5, 17
	s_add_u32 s4, s82, 0xe0800
	s_addc_u32 s5, s83, 0
	v_writelane_b32 v249, s4, 18
	v_mov_b64_e32 v[144:145], 0x7f
	v_mov_b32_e32 v178, 0x41b17218
	v_writelane_b32 v249, s5, 19
	s_add_u32 s4, s82, 0xe0900
	s_addc_u32 s5, s83, 0
	v_writelane_b32 v249, s4, 20
	v_mov_b64_e32 v[146:147], 0xa00
	v_mov_b64_e32 v[148:149], 0x9ff
	v_writelane_b32 v249, s5, 21
	s_add_u32 s4, s82, 0xe0a00
	s_addc_u32 s5, s83, 0
	v_writelane_b32 v249, s4, 22
	v_mov_b32_e32 v179, 0x7fc80000
	v_mov_b64_e32 v[150:151], 0xb00
	v_writelane_b32 v249, s5, 23
	s_add_u32 s4, s82, 0xe0b00
	s_addc_u32 s5, s83, 0
	v_writelane_b32 v249, s4, 24
	v_mov_b64_e32 v[152:153], 0xaff
	v_mov_b32_e32 v180, 0x7f800000
	v_writelane_b32 v249, s5, 25
	s_add_u32 s4, s82, 0xe0c00
	s_addc_u32 s5, s83, 0
	v_writelane_b32 v249, s4, 26
	v_mov_b32_e32 v192, v137
	v_mov_b32_e32 v193, v137
	v_writelane_b32 v249, s5, 27
	s_add_u32 s4, s82, 0xe0d00
	s_addc_u32 s5, s83, 0
	v_writelane_b32 v249, s4, 28
	s_movk_i32 s92, 0x37ff
	s_mov_b64 s[76:77], 0x40000
	v_writelane_b32 v249, s5, 29
	s_add_u32 s4, s82, 0xe0e00
	s_addc_u32 s5, s83, 0
	v_writelane_b32 v249, s4, 30
	s_nop 1
	v_writelane_b32 v249, s5, 31
	s_add_u32 s4, s82, 0xe0f00
	s_addc_u32 s5, s83, 0
	v_writelane_b32 v249, s4, 32
	s_nop 1
	v_writelane_b32 v249, s5, 33
	s_add_u32 s4, s82, 0xe1000
	s_addc_u32 s5, s83, 0
	v_writelane_b32 v249, s4, 34
	s_nop 1
	v_writelane_b32 v249, s5, 35
	s_add_u32 s4, s82, 0xe1100
	s_addc_u32 s5, s83, 0
	v_writelane_b32 v249, s4, 36
	s_nop 1
	v_writelane_b32 v249, s5, 37
	s_add_u32 s4, s82, 0xe1200
	s_addc_u32 s5, s83, 0
	v_writelane_b32 v249, s4, 38
	s_nop 1
	v_writelane_b32 v249, s5, 39
	s_add_u32 s4, s82, 0xe1300
	s_addc_u32 s5, s83, 0
	v_writelane_b32 v249, s4, 40
	s_cmp_eq_u32 s3, 15
	s_nop 0
	v_writelane_b32 v249, s5, 41
	s_cselect_b64 s[4:5], -1, 0
	v_writelane_b32 v249, s4, 42
	s_cmp_eq_u32 s3, 14
	s_nop 0
	v_writelane_b32 v249, s5, 43
	s_cselect_b64 s[4:5], -1, 0
	v_writelane_b32 v249, s4, 44
	s_cmp_eq_u32 s3, 13
	s_nop 0
	v_writelane_b32 v249, s5, 45
	s_cselect_b64 s[4:5], -1, 0
	v_writelane_b32 v249, s4, 46
	s_cmp_eq_u32 s3, 12
	s_nop 0
	v_writelane_b32 v249, s5, 47
	s_cselect_b64 s[4:5], -1, 0
	v_writelane_b32 v249, s4, 48
	s_cmp_eq_u32 s3, 11
	s_nop 0
	v_writelane_b32 v249, s5, 49
	s_cselect_b64 s[4:5], -1, 0
	v_writelane_b32 v249, s4, 50
	s_cmp_eq_u32 s3, 10
	s_nop 0
	v_writelane_b32 v249, s5, 51
	s_cselect_b64 s[4:5], -1, 0
	v_writelane_b32 v249, s4, 52
	s_cmp_eq_u32 s3, 9
	s_nop 0
	v_writelane_b32 v249, s5, 53
	s_cselect_b64 s[4:5], -1, 0
	v_writelane_b32 v249, s4, 54
	s_cmp_eq_u32 s3, 8
	s_nop 0
	v_writelane_b32 v249, s5, 55
	s_cselect_b64 s[4:5], -1, 0
	v_writelane_b32 v249, s4, 56
	s_cmp_eq_u32 s3, 7
	s_nop 0
	v_writelane_b32 v249, s5, 57
	s_cselect_b64 s[4:5], -1, 0
	v_writelane_b32 v249, s4, 58
	s_cmp_eq_u32 s3, 6
	s_nop 0
	v_writelane_b32 v249, s5, 59
	s_cselect_b64 s[4:5], -1, 0
	v_writelane_b32 v249, s4, 60
	s_cmp_eq_u32 s3, 5
	s_nop 0
	v_writelane_b32 v249, s5, 61
	s_cselect_b64 s[4:5], -1, 0
	v_writelane_b32 v249, s4, 62
	s_cmp_eq_u32 s3, 4
	s_nop 0
	v_writelane_b32 v249, s5, 63
	s_cselect_b64 s[4:5], -1, 0
	v_writelane_b32 v250, s4, 0
	s_cmp_eq_u32 s3, 3
	s_nop 0
	v_writelane_b32 v250, s5, 1
	s_cselect_b64 s[4:5], -1, 0
	v_writelane_b32 v250, s4, 2
	s_cmp_eq_u32 s3, 2
	s_nop 0
	v_writelane_b32 v250, s5, 3
	s_cselect_b64 s[4:5], -1, 0
	v_writelane_b32 v250, s4, 4
	s_cmp_eq_u32 s3, 1
	s_nop 0
	v_writelane_b32 v250, s5, 5
	s_cselect_b64 s[4:5], -1, 0
	v_writelane_b32 v250, s4, 6
	s_cmp_eq_u32 s3, 0
	s_nop 0
	v_writelane_b32 v250, s5, 7
	s_cselect_b64 s[4:5], -1, 0
	s_lshl_b32 s3, s3, 8
	v_writelane_b32 v250, s4, 8
	s_add_u32 s3, s12, s3
	s_nop 0
	v_writelane_b32 v250, s5, 9
	s_addc_u32 s4, s13, 0
	s_add_u32 s6, s3, 0x1400
	s_addc_u32 s7, s4, 0
	v_writelane_b32 v250, s6, 10
	s_nop 1
	v_writelane_b32 v250, s7, 11
	s_add_u32 s6, s3, 0x2400
	s_addc_u32 s7, s4, 0
	v_writelane_b32 v250, s6, 12
	s_add_u32 s4, s82, 0xe3400
	s_addc_u32 s5, s83, 0
	v_writelane_b32 v250, s7, 13
	v_writelane_b32 v250, s4, 14
	s_nop 1
	v_writelane_b32 v250, s5, 15
	s_add_u32 s4, s82, 0xe3500
	s_addc_u32 s5, s83, 0
	s_add_u32 s42, s82, 0x16800000
	s_addc_u32 s43, s83, 0
	s_add_u32 s28, s82, 0x9d00000
	s_addc_u32 s29, s83, 0
	s_add_u32 s90, s82, 0xe800000
	s_addc_u32 s91, s83, 0
	v_writelane_b32 v250, s4, 16
	s_cmpk_lt_i32 s2, 0x200
	s_nop 0
	v_writelane_b32 v250, s5, 17
	s_cselect_b64 s[4:5], -1, 0
	v_writelane_b32 v250, s4, 18
	s_ashr_i32 s3, s2, 31
	s_nop 0
	v_writelane_b32 v250, s5, 19
	s_lshr_b32 s4, s3, 29
	s_add_i32 s4, s2, s4
	s_ashr_i32 s7, s4, 3
	s_and_b32 s4, s4, -8
	s_sub_i32 s8, s2, s4
	s_lshl_b32 s9, s8, 6
	s_add_u32 s62, s82, 0x12800000
	s_addc_u32 s63, s83, 0
	s_add_u32 s30, s82, 0x9500000
	s_addc_u32 s31, s83, 0
	s_add_u32 s4, s82, 0x1e802000
	v_writelane_b32 v250, s4, 20
; __device__ __forceinline__ void gla_out_load(const Args& a, int unit, int tid, OutIn& r) {
;     const int bh = unit >> 6, n = unit & 63, b = bh >> 2, h = bh & 3, t0 = b * SEQ + n * 64;
;     const bf16_t* Z = (const bf16_t*)(a.ws + WS_Z); const float* BCG = (const float*)(a.ws + WS_BCG);
; #pragma unroll
;     for (int i = 0; i < 2; ++i) { const int p = tid + 512 * i, j = p >> 4, d0 = (p & 15) * 8; const bf16_t* rp = Z + (size_t)(t0 + j) * ZW + h * 128 + d0;
;         r.q[i] = *(const u32x4*)(rp + ZC_Q); r.k[i] = *(const u32x4*)(rp + ZC_K);
;         r.bc[i][0] = *(const f32x4*)(BCG + (size_t)(t0 + j) * 512 + h * 128 + d0); r.bc[i][1] = *(const f32x4*)(BCG + (size_t)(t0 + j) * 512 + h * 128 + d0 + 4);
;         r.bm[i][0] = *(const f32x4*)(BCG + (size_t)(t0 + 31) * 512 + h * 128 + d0); r.bm[i][1] = *(const f32x4*)(BCG + (size_t)(t0 + 31) * 512 + h * 128 + d0 + 4); }
; #pragma unroll
;     for (int i = 0; i < 4; ++i) r.v[i] = *(const u32x4*)(Z + (size_t)(t0 + 4 * (tid >> 5) + i) * ZW + ZC_V + h * 256 + (tid & 31) * 8);
; }
; __device__ __forceinline__ void gla_out_unit(const Args& a, int l, unsigned char* lds, int unit, int next, int tid, OutIn& in) {
;     const int lane = tid & 63, wave = tid >> 6, r16 = lane & 15, quad = lane >> 4;
;     const int bh = unit >> 6, n = unit & 63, b = bh >> 2, h = bh & 3, t0 = b * SEQ + n * 64;
; __device__ __forceinline__ void ssm_out_unit(const Args& a, int unit) {
;     const int tid = otid(), lane = tid & 63, wave = tid >> 6, r16 = lane & 15, quad = lane >> 4;
;     const int g = unit >> 4, cb = unit & 15;
;     const bf16_t* XS = (const bf16_t*)(a.ws + WS_XS); const bf16_t* KT = (const bf16_t*)(a.ws + WS_KT); const bf16_t* MCT = (const bf16_t*)(a.ws + WS_MCT);
;     const bf16_t* HC = (const bf16_t*)(a.ws + WS_HC); bf16_t* YS = (bf16_t*)(a.ws + WS_YS);
;     const int ch = (quad & 1) * 8, jo = quad >> 1;
;     f32x4 acc[2][4];
; #pragma unroll
;     for (int i = 0; i < 2; ++i)
; #pragma unroll
;         for (int k = 0; k < 4; ++k) acc[i][k] = (f32x4){0.f, 0.f, 0.f, 0.f};
;     const int kbn = cb * 2 + 2;
;     const bf16x8 zero8 = (bf16x8){0, 0, 0, 0, 0, 0, 0, 0};
;     for (int kb0 = 0; kb0 < kbn; kb0 += 4) {
;         bf16x8 af[4][2], bf[4][4];
; #pragma unroll
;         for (int u = 0; u < 4; ++u) {
;             const int kb = kb0 + u, jp = kb * 2 + jo; const bool on = kb < kbn;
; #pragma unroll
	s_addc_u32 s4, s83, 0
	s_add_u32 s74, s82, 0x1b00000
	s_addc_u32 s75, s83, 0
	s_add_u32 s34, s82, 0xa500000
	s_addc_u32 s35, s83, 0
	s_cmpk_lt_i32 s2, 0x80
	v_writelane_b32 v250, s4, 21
	s_cselect_b64 s[4:5], -1, 0
	s_lshl_b32 s10, s8, 4
	v_writelane_b32 v250, s4, 22
	s_cmpk_gt_u32 s2, 0x7f
	s_nop 0
	v_writelane_b32 v250, s5, 23
	s_cselect_b64 s[4:5], -1, 0
	s_lshl_b32 s11, s2, 1
	v_writelane_b32 v250, s4, 24
	s_add_i32 s12, s11, 0x200
	s_nop 0
	v_writelane_b32 v250, s5, 25
	s_lshl_b32 s4, s12, 4
	s_lshl_b32 s5, s2, 7
	s_and_b32 s4, s4, 0xfffff000
	v_writelane_b32 v250, s5, 26
	s_and_b32 s5, s5, 0xf80
	s_or_b32 s6, s4, s5
	s_bfe_u32 s4, s2, 0x20005
	s_add_u32 s66, s82, 0x1e800000
	s_addc_u32 s67, s83, 0
	s_add_u32 s22, s82, 0x32800000
	s_addc_u32 s23, s83, 0
	s_lshl_b32 s5, s4, 8
	s_add_u32 s14, s66, s5
	s_addc_u32 s15, s67, 0
	v_writelane_b32 v250, s14, 27
	s_lshl_b32 s4, s4, 9
	s_nop 0
	v_writelane_b32 v250, s15, 28
	s_add_u32 s14, s22, s4
	s_addc_u32 s15, s23, 0
	v_writelane_b32 v250, s14, 29
	s_nop 1
	v_writelane_b32 v250, s15, 30
	s_or_b32 s14, s6, 31
	s_ashr_i32 s15, s14, 31
	s_lshl_b64 s[14:15], s[14:15], 11
	s_add_u32 s5, s22, s14
	v_writelane_b32 v250, s6, 31
	s_addc_u32 s6, s23, s15
	s_add_u32 s14, s5, s4
	s_addc_u32 s15, s6, 0
	v_writelane_b32 v250, s14, 32
	s_nop 1
	v_writelane_b32 v250, s15, 33
	s_add_i32 s14, s11, 0x201
	s_add_u32 s24, s82, 0x1a800000
	v_writelane_b32 v250, s11, 34
	s_addc_u32 s25, s83, 0
	v_writelane_b32 v250, s24, 35
	s_ashr_i32 s13, s12, 31
	s_lshl_b64 s[12:13], s[12:13], 8
	v_writelane_b32 v250, s25, 36
	s_lshl_b32 s36, s2, 3
	v_writelane_b32 v250, s12, 37
	s_and_b32 s5, s36, 0x300
	s_cmp_gt_i32 s14, -1
	v_writelane_b32 v250, s13, 38
	v_writelane_b32 v250, s5, 39
	s_cselect_b64 s[12:13], -1, 0
	s_lshl_b32 s5, s14, 6
	s_lshl_b32 s11, s14, 4
	v_writelane_b32 v250, s12, 40
	s_and_b32 s6, s5, 0xfc0
	s_and_b32 s5, s11, 0x7ffff000
	v_writelane_b32 v250, s13, 41
	s_or_b32 s13, s5, s6
	s_bfe_u32 s5, s14, 0x20006
	s_lshl_b32 s12, s5, 8
	s_add_u32 s24, s66, s12
	s_addc_u32 s25, s67, 0
	v_writelane_b32 v250, s24, 42
	s_lshl_b32 s5, s5, 9
	s_nop 0
	v_writelane_b32 v250, s25, 43
	s_add_u32 s24, s22, s5
	s_addc_u32 s25, s23, 0
	v_writelane_b32 v250, s24, 44
	s_or_b32 s88, s13, 31
	s_nop 0
	v_writelane_b32 v250, s25, 45
	v_writelane_b32 v250, s13, 46
	s_lshl_b64 s[12:13], s[88:89], 11
	s_add_u32 s12, s22, s12
	s_addc_u32 s13, s23, s13
	s_add_u32 s12, s12, s5
	s_addc_u32 s13, s13, 0
	v_writelane_b32 v250, s12, 47
	s_and_b32 s11, s11, 0xfffff000
	s_or_b32 s6, s11, s6
	v_writelane_b32 v250, s13, 48
	v_writelane_b32 v250, s6, 49
	s_lshl_b32 s6, s2, 4
	v_writelane_b32 v250, s6, 50
	s_lshl_b32 s11, s2, 6
	s_and_b32 s6, s6, 0xfffff000
	v_writelane_b32 v250, s11, 51
	s_and_b32 s11, s11, 0xfc0
	s_ashr_i32 s15, s14, 31
	s_or_b32 s12, s6, s11
	s_lshl_b32 s6, s14, 2
	s_lshl_b64 s[14:15], s[14:15], 8
	v_writelane_b32 v250, s14, 52
	s_and_b32 s6, s6, 0x300
	s_nop 0
	v_writelane_b32 v250, s15, 53
	v_writelane_b32 v250, s6, 54
	s_bfe_u32 s6, s2, 0x20006
	s_lshl_b32 s11, s6, 7
	v_writelane_b32 v250, s11, 55
	s_lshl_b32 s11, s6, 8
	s_add_u32 s14, s66, s11
	s_addc_u32 s15, s67, 0
	v_writelane_b32 v250, s14, 56
	s_lshl_b32 s6, s6, 9
	s_nop 0
	v_writelane_b32 v250, s15, 57
	s_add_u32 s14, s22, s6
	s_addc_u32 s15, s23, 0
	v_writelane_b32 v250, s14, 58
	s_nop 1
	v_writelane_b32 v250, s15, 59
	v_writelane_b32 v250, s12, 60
	s_or_b32 s12, s12, 31
	s_ashr_i32 s13, s12, 31
	s_lshl_b64 s[12:13], s[12:13], 11
	s_add_u32 s11, s22, s12
	v_writelane_b32 v250, s22, 61
	s_addc_u32 s12, s23, s13
	s_add_u32 s14, s11, s6
	s_addc_u32 s15, s12, 0
	v_writelane_b32 v250, s23, 62
	s_cmpk_lt_i32 s2, 0x300
	v_writelane_b32 v250, s14, 63
	s_cselect_b64 s[12:13], -1, 0
	s_ashr_i32 s68, s2, 4
	v_writelane_b32 v251, s15, 0
	v_writelane_b32 v251, s12, 1
	s_add_u32 s14, s82, 0x400000
	s_addc_u32 s15, s83, 0
	v_writelane_b32 v251, s13, 2
	v_writelane_b32 v251, s14, 3
	s_and_b32 s11, s2, 15
	s_nop 0
	v_writelane_b32 v251, s15, 4
	s_add_u32 s14, s82, 0x34800000
	s_addc_u32 s15, s83, 0
	v_writelane_b32 v251, s14, 5
	s_lshl_b32 s33, s11, 1
	s_ashr_i32 s69, s68, 31
	v_writelane_b32 v251, s15, 6
	s_add_i32 s14, s33, 2
	s_lshl_b32 s25, s11, 2
	s_lshl_b32 s93, s68, 6
	v_writelane_b32 v251, s14, 7
	s_add_u32 s14, s82, 0x1300000
	s_addc_u32 s15, s83, 0
	v_writelane_b32 v251, s14, 8
	s_add_u32 s22, s82, 0x900000
	s_addc_u32 s23, s83, 0
	v_writelane_b32 v251, s15, 9
	s_lshl_b64 s[14:15], s[68:69], 8
	s_add_u32 s14, s22, s14
	s_addc_u32 s15, s23, s15
	v_writelane_b32 v251, s14, 10
	s_lshl_b32 s11, s11, 6
	s_or_b32 s24, s11, 16
	v_writelane_b32 v251, s15, 11
	v_writelane_b32 v251, s24, 12
	s_or_b32 s24, s11, 32
	s_and_b32 s14, s2, -16
	v_writelane_b32 v251, s24, 13
	s_ashr_i32 s15, s14, 31
	v_writelane_b32 v251, s11, 14
	s_or_b32 s11, s11, 48
	s_lshl_b64 s[14:15], s[14:15], 1
	v_writelane_b32 v251, s11, 15
	s_lshl_b64 s[38:39], s[68:69], 10
	v_writelane_b32 v251, s38, 16
	s_add_u32 s14, s74, s14
	s_addc_u32 s15, s75, s15
	v_writelane_b32 v251, s39, 17
	v_writelane_b32 v251, s14, 18
	s_xor_b32 s11, s2, 15
	s_add_i32 s24, s11, 0x100
	v_writelane_b32 v251, s15, 19
	v_writelane_b32 v251, s20, 20
	s_and_b32 s11, s11, 15
	s_ashr_i32 s72, s24, 4
	v_writelane_b32 v251, s21, 21
	s_or_b32 s20, s25, 1
	v_writelane_b32 v251, s20, 22
	s_or_b32 s20, s25, 2
	v_writelane_b32 v251, s20, 23
	v_writelane_b32 v251, s25, 24
	s_or_b32 s20, s25, 3
	s_lshl_b32 s95, s11, 1
	s_ashr_i32 s73, s72, 31
	v_writelane_b32 v251, s20, 25
	s_add_i32 s20, s95, 2
	v_writelane_b32 v251, s20, 26
	s_lshl_b32 s25, s11, 2
	s_lshl_b32 s97, s72, 6
	s_lshl_b64 s[20:21], s[72:73], 8
	s_add_u32 s20, s22, s20
	s_addc_u32 s21, s23, s21
;     __device__ bool next(int i, Unit& u) const { const bool ok = StaticOrder::next(i / 3, u); u.seg = i % 3; return ok; }
;     __device__ bool next(int i, Unit& u) const {
;         const long L = (long)i * G + c; if (L >= nwg) return false;
;         int wgid = (int)L; { const int q = nwg / NXCD, r = nwg % NXCD, xcd = wgid % NXCD, off = wgid / NXCD; wgid = (xcd < r ? xcd * (q + 1) : r * (q + 1) + (xcd - r) * q) + off; }
;         const int nig = WGM * nN, gid = wgid / nig, fm = gid * WGM, gsz = (nM - fm) < WGM ? (nM - fm) : WGM;
;         u.pm = fm + ((wgid % nig) % gsz); u.pn = (wgid % nig) / gsz; u.seg = 0; return true;
;     }
; __device__ __forceinline__ void phase_prep(const Args& a, int l, unsigned char* lds, int G) {
;     ...
;     const float* f1n = a.in[I_F1N] + (size_t)l * DM; const float* f2n = a.in[I_F2N] + (size_t)l * DM; const float* mxn = a.in[I_MIXN] + (size_t)l * DM;
;     const float* f1g = a.in[I_F1G] + (size_t)l * DM * FF; const float* f1u = a.in[I_F1U] + (size_t)l * DM * FF; const float* f1d = a.in[I_F1D] + (size_t)l * FF * DM;
;     const float* f2g = a.in[I_F2G] + (size_t)l * DM * FF; const float* f2u = a.in[I_F2U] + (size_t)l * DM * FF; const float* f2d = a.in[I_F2D] + (size_t)l * FF * DM;
;     const float* win = a.in[I_WIN] + (size_t)l * DM * INW; const float* wbr = a.in[I_WBR] + (size_t)l * DM * DM; const float* wout = a.in[I_WOUT] + (size_t)l * DM * DM;
;     const float* wglu = a.in[I_WGLU] + (size_t)l * 512 * 512;
;     constexpr int IT_FU = (DM / 64) * (FF / 64), IT_FD = (FF / 64) * (DM / 64), IT_WA = (DM / 64) * (3584 / 64), IT_WB = (DM / 64) * (6656 / 64),
;                   IT_BR = (1536 / 64) * (DM / 64), IT_WO = (DM / 64) * (DM / 64), IT_GL = (512 / 64) * (512 / 64);
;     constexpr int IT_TOTAL = 4 * IT_FU + 2 * IT_FD + IT_WA + IT_WB + IT_BR + IT_WO + IT_GL;
	v_writelane_b32 v251, s20, 27
	s_lshl_b32 s11, s11, 6
	s_or_b32 s22, s11, 16
	v_writelane_b32 v251, s21, 28
	v_writelane_b32 v251, s22, 29
	s_or_b32 s22, s11, 32
	s_and_b32 s20, s24, -16
	v_writelane_b32 v251, s22, 30
	s_ashr_i32 s21, s20, 31
	v_writelane_b32 v251, s11, 31
	s_or_b32 s11, s11, 48
	s_lshl_b64 s[20:21], s[20:21], 1
	v_writelane_b32 v251, s11, 32
	s_lshl_b64 s[22:23], s[72:73], 10
	v_writelane_b32 v251, s22, 33
	s_add_u32 s20, s74, s20
	s_addc_u32 s21, s75, s21
	v_writelane_b32 v251, s23, 34
	v_writelane_b32 v251, s20, 35
	s_or_b32 s11, s25, 1
	s_lshl_b32 s38, s2, 9
	v_writelane_b32 v251, s21, 36
	v_writelane_b32 v251, s11, 37
	s_or_b32 s11, s25, 2
	v_writelane_b32 v251, s11, 38
	s_or_b32 s11, s25, 3
	v_writelane_b32 v251, s25, 39
	s_add_u32 s20, s82, 0x500000
	v_writelane_b32 v251, s11, 40
	s_addc_u32 s21, s83, 0
	v_writelane_b32 v251, s20, 41
	s_nop 1
	v_writelane_b32 v251, s21, 42
	s_add_u32 s20, s82, 0x120000
	s_addc_u32 s21, s83, 0
	v_writelane_b32 v251, s20, 43
	s_nop 1
	v_writelane_b32 v251, s21, 44
	s_add_u32 s20, s82, 0x200000
	s_addc_u32 s21, s83, 0
	v_writelane_b32 v251, s20, 45
	s_cmpk_lt_i32 s2, 0x400
	s_nop 0
	v_writelane_b32 v251, s21, 46
	s_cselect_b64 s[20:21], -1, 0
	s_add_u32 s70, s82, 0xb00000
	v_writelane_b32 v251, s20, 47
	s_addc_u32 s71, s83, 0
	s_lshl_b32 s11, s2, 5
	v_writelane_b32 v251, s21, 48
	s_and_b32 s11, s11, 0xe0
	s_ashr_i32 s20, s2, 3
	v_writelane_b32 v251, s11, 49
	s_lshl_b32 s11, s20, 7
	s_ashr_i32 s21, s20, 31
	v_writelane_b32 v251, s11, 50
	v_writelane_b32 v251, s20, 51
	s_mul_i32 s11, s8, 0x41
	s_nop 0
	v_writelane_b32 v251, s21, 52
	s_lshl_b64 s[20:21], s[20:21], 14
	s_add_u32 s40, s82, 0x6d00000
	s_addc_u32 s41, s83, 0
	v_writelane_b32 v251, s20, 53
	s_cmpk_lt_i32 s2, 0xa00
	s_nop 0
	v_writelane_b32 v251, s21, 54
	s_cselect_b64 s[20:21], -1, 0
	v_writelane_b32 v251, s20, 55
	s_nop 1
	v_writelane_b32 v251, s21, 56
	s_add_u32 s20, s82, 0x100000
	s_addc_u32 s21, s83, 0
	v_writelane_b32 v251, s20, 57
	s_cmpk_lt_i32 s2, 0xb00
	s_nop 0
	v_writelane_b32 v251, s21, 58
	s_cselect_b64 s[20:21], -1, 0
	v_writelane_b32 v251, s20, 59
	s_nop 1
	v_writelane_b32 v251, s21, 60
	s_add_u32 s20, s82, 0x2b00000
	s_addc_u32 s21, s83, 0
	v_writelane_b32 v251, s20, 61
	s_waitcnt lgkmcnt(0)
	s_cmp_lg_u64 s[46:47], 0
	v_writelane_b32 v251, s21, 62
	s_cselect_b64 s[20:21], -1, 0
	v_writelane_b32 v251, s20, 63
	s_nop 1
	v_writelane_b32 v252, s21, 0
	s_add_u32 s20, s82, 0xa600000
	s_addc_u32 s21, s83, 0
	v_writelane_b32 v252, s20, 1
	s_nop 1
	v_writelane_b32 v252, s21, 2
	s_load_dwordx16 s[12:27], s[0:1], 0x80
	s_waitcnt lgkmcnt(0)
	s_cmp_lg_u64 s[26:27], 0
	s_cselect_b64 s[20:21], -1, 0
	v_writelane_b32 v252, s20, 3
	s_mov_b32 s26, 0x1e801000
	s_nop 0
	v_writelane_b32 v252, s21, 4
	s_add_u32 s20, s82, 0x5700000
	s_addc_u32 s21, s83, 0
	v_writelane_b32 v252, s20, 5
	s_nop 1
	v_writelane_b32 v252, s21, 6
	s_add_u32 s20, s82, 0xd200000
	s_addc_u32 s21, s83, 0
	v_writelane_b32 v252, s20, 7
	s_cmp_lg_u64 s[54:55], 0
	s_nop 0
	v_writelane_b32 v252, s21, 8
	s_cselect_b64 s[20:21], -1, 0
	v_writelane_b32 v252, s20, 9
	s_nop 1
	v_writelane_b32 v252, s21, 10
	s_add_u32 s20, s82, 0x9500400
	s_addc_u32 s21, s83, 0
	v_writelane_b32 v252, s20, 11
	s_ashr_i32 s37, s36, 31
	s_nop 0
	v_writelane_b32 v252, s21, 12
	s_or_b32 s20, s36, 1
	s_ashr_i32 s21, s20, 31
	s_lshl_b64 s[20:21], s[20:21], 12
	v_writelane_b32 v252, s20, 13
	s_nop 1
	v_writelane_b32 v252, s21, 14
	s_or_b32 s20, s36, 2
	s_ashr_i32 s21, s20, 31
	s_lshl_b64 s[20:21], s[20:21], 12
	v_writelane_b32 v252, s20, 15
	s_nop 1
	v_writelane_b32 v252, s21, 16
	s_or_b32 s20, s36, 3
	s_ashr_i32 s21, s20, 31
	s_lshl_b64 s[20:21], s[20:21], 12
	v_writelane_b32 v252, s20, 17
	s_nop 1
	v_writelane_b32 v252, s21, 18
	s_or_b32 s20, s36, 4
	s_ashr_i32 s21, s20, 31
	s_lshl_b64 s[20:21], s[20:21], 12
	v_writelane_b32 v252, s20, 19
	s_nop 1
	v_writelane_b32 v252, s21, 20
	s_or_b32 s20, s36, 5
	s_ashr_i32 s21, s20, 31
	s_lshl_b64 s[20:21], s[20:21], 12
	v_writelane_b32 v252, s20, 21
	s_nop 1
	v_writelane_b32 v252, s21, 22
	s_or_b32 s20, s36, 6
	s_ashr_i32 s21, s20, 31
	s_lshl_b64 s[20:21], s[20:21], 12
	v_writelane_b32 v252, s20, 23
	s_nop 1
	v_writelane_b32 v252, s21, 24
	s_or_b32 s20, s36, 7
	s_ashr_i32 s21, s20, 31
	s_lshl_b64 s[20:21], s[20:21], 12
	v_writelane_b32 v252, s20, 25
	s_nop 1
	v_writelane_b32 v252, s21, 26
	s_lshl_b64 s[20:21], s[36:37], 12
	v_writelane_b32 v252, s20, 27
	s_cmpk_lt_i32 s2, 0x120
	s_nop 0
	v_writelane_b32 v252, s21, 28
	s_cselect_b64 s[20:21], -1, 0
	s_cmp_lt_i32 s8, 0
	s_cselect_b32 s9, s11, s9
	s_mul_i32 s11, s8, 17
	v_writelane_b32 v252, s20, 29
	s_cselect_b32 s10, s11, s10
	s_movk_i32 s11, 0x141
	v_writelane_b32 v252, s21, 30
	s_cselect_b32 s21, s11, 0x140
	s_movk_i32 s11, 0x161
	s_cselect_b32 s24, s11, 0x160
	s_add_i32 s9, s9, s7
	s_ashr_i32 s11, s9, 31
	s_lshr_b32 s11, s11, 27
	s_add_i32 s11, s9, s11
	s_and_b32 s20, s11, 0xffe0
	s_sub_i32 s9, s9, s20
	s_bfe_i32 s20, s9, 0x80000
	s_bfe_u32 s20, s20, 0x2000d
	s_add_i32 s20, s9, s20
	s_and_b32 s22, s20, 0xfc
	s_add_i32 s10, s10, s7
	s_sub_i32 s9, s9, s22
	s_ashr_i32 s22, s10, 31
	s_lshr_b32 s22, s22, 29
	s_add_i32 s22, s10, s22
	s_and_b32 s23, s22, 0xfff8
	s_sub_i32 s10, s10, s23
	s_bfe_i32 s23, s10, 0x80000
	s_bfe_u32 s23, s23, 0x2000d
	s_add_i32 s23, s10, s23
	s_ashr_i32 s11, s11, 5
	s_and_b32 s27, s23, 0xfc
	s_lshl_b32 s11, s11, 2
	s_sext_i32_i8 s9, s9
	s_sub_i32 s10, s10, s27
	s_add_i32 s60, s11, s9
	s_ashr_i32 s9, s22, 3
	s_bfe_i32 s11, s23, 0x80000
	s_bfe_i32 s20, s20, 0x80000
	s_lshl_b32 s9, s9, 2
	s_sext_i32_i16 s11, s11
	s_sext_i32_i8 s10, s10
	s_sext_i32_i16 s20, s20
	s_add_i32 s64, s9, s10
;     __device__ bool next(int i, Unit& u) const { const bool ok = StaticOrder::next(i / 3, u); u.seg = i % 3; return ok; }
; #define PG8_STAGE(bufoff, gbase, voff) do { _Pragma("unroll") for (int _i = 0; _i < 2; ++_i) \
;         __builtin_amdgcn_global_load_lds((const unsigned*)((const char*)(gbase) + (voff)[_i]), (LAS unsigned*)(lds + (bufoff) + ldsw + _i * 8192), 16, 0, PG8_AUX); } while (0)
; #define PG8_WAIT_V(n) asm volatile("s_waitcnt vmcnt(" #n ")" ::: "memory")
; #define PG8_BAR __builtin_amdgcn_s_barrier()
;     __device__ bool next(int i, Unit& u) const {
;         const long L = (long)i * G + c; if (L >= nwg) return false;
;         int wgid = (int)L; { const int q = nwg / NXCD, r = nwg % NXCD, xcd = wgid % NXCD, off = wgid / NXCD; wgid = (xcd < r ? xcd * (q + 1) : r * (q + 1) + (xcd - r) * q) + off; }
;         const int nig = WGM * nN, gid = wgid / nig, fm = gid * WGM, gsz = (nM - fm) < WGM ? (nM - fm) : WGM;
;         u.pm = fm + ((wgid % nig) % gsz); u.pn = (wgid % nig) / gsz; u.seg = 0; return true;
;     }
; template <class Epi, class Sched>
; __device__ __forceinline__ void gemm_phase(LAS unsigned char* lds, const Gemm g, const Sched& S, const Epi& E) {
;     ...
;     const char* cA = (const char*)g.A + (size_t)(g.fix ? 0 : cur.pm) * tstepA + (size_t)S.koff(cur) * 2; const char* cB = (const char*)g.Bt + (size_t)(g.fix ? 0 : cur.pn) * tstepB + (size_t)S.koff(cur) * 2;
;     ...
;     PG8_STAGE(PG8_SB(0, 0), cB, voffB); PG8_STAGE(PG8_SB(0, 1), cB + hstepB, voffB); PG8_STAGE(PG8_SA(0, 0), cA, voffA); PG8_STAGE(PG8_SA(0, 1), cA + hstepA, voffA);
;     if (wr == 1) PG8_BAR;
;     PG8_WAIT_V(2); PG8_BAR;
;     PG8_STAGE(PG8_SB(1, 0), cB + kstep, voffB); PG8_STAGE(PG8_SA(1, 0), cA + kstep, voffA); PG8_STAGE(PG8_SB(1, 1), cB + hstepB + kstep, voffB);
	s_ashr_i32 s9, s11, 2
	v_writelane_b32 v252, s9, 31
	s_ashr_i32 s9, s20, 2
	s_lshr_b32 s10, s11, 2
	v_writelane_b32 v252, s9, 32
	s_mov_b32 s22, s64
	s_ashr_i32 s65, s64, 31
	s_bfe_i64 s[10:11], s[10:11], 0x100000
	v_writelane_b32 v252, s22, 33
	s_lshl_b64 s[10:11], s[10:11], 18
	s_lshr_b32 s20, s20, 2
	v_writelane_b32 v252, s23, 34
	s_lshl_b64 s[22:23], s[64:65], 18
	s_add_u32 s10, s34, s10
	v_writelane_b32 v252, s34, 35
	s_addc_u32 s11, s35, s11
	s_mul_i32 s9, s8, s21
	v_writelane_b32 v252, s35, 36
	s_add_u32 s34, s10, 0x20000
	s_addc_u32 s35, s11, 0
	v_writelane_b32 v252, s34, 37
	s_add_u32 s22, s74, s22
	s_addc_u32 s23, s75, s23
	v_writelane_b32 v252, s35, 38
	s_add_u32 s34, s22, 0x20000
	v_writelane_b32 v252, s22, 39
	s_addc_u32 s35, s23, 0
	s_mul_i32 s8, s8, s24
	v_writelane_b32 v252, s23, 40
	v_writelane_b32 v252, s34, 41
	s_add_u32 s22, s10, 0x20080
	s_nop 0
	v_writelane_b32 v252, s35, 42
	v_writelane_b32 v252, s10, 43
	s_addc_u32 s23, s11, 0
	s_add_i32 s9, s9, s7
	v_writelane_b32 v252, s11, 44
	s_mul_hi_i32 s10, s9, 0x66666667
	s_lshr_b32 s11, s10, 31
	s_ashr_i32 s10, s10, 6
	s_add_i32 s10, s10, s11
	s_mul_i32 s11, s10, 0xa0
	s_sub_i32 s9, s9, s11
	s_bfe_u32 s11, s9, 0x2001d
	s_add_i32 s11, s9, s11
	s_add_i32 s8, s8, s7
	s_and_b32 s21, s11, 0xfffc
	s_mul_hi_i32 s7, s8, 0x2e8ba2e9
	s_sub_i32 s9, s9, s21
	s_lshr_b32 s21, s7, 31
	s_ashr_i32 s7, s7, 5
	s_add_i32 s7, s7, s21
	s_mul_i32 s21, s7, 0xb0
	s_sub_i32 s8, s8, s21
	s_bfe_u32 s21, s8, 0x2001d
	v_writelane_b32 v252, s22, 45
	s_add_i32 s21, s8, s21
	s_lshl_b32 s10, s10, 2
	v_writelane_b32 v252, s23, 46
	s_and_b32 s22, s21, 0xfffc
	s_sub_i32 s8, s8, s22
	s_sext_i32_i16 s9, s9
	s_add_i32 s22, s10, s9
	s_lshl_b32 s7, s7, 2
	s_sext_i32_i16 s9, s21
	s_sext_i32_i16 s8, s8
	s_add_i32 s24, s7, s8
	s_lshr_b32 s8, s9, 2
	s_ashr_i32 s7, s9, 2
	s_bfe_i64 s[8:9], s[8:9], 0x100000
	v_writelane_b32 v252, s7, 47
	s_lshl_b64 s[8:9], s[8:9], 20
	s_sext_i32_i16 s11, s11
	v_writelane_b32 v252, s8, 48
	s_ashr_i32 s7, s11, 2
	s_mov_b32 s10, s24
	v_writelane_b32 v252, s9, 49
	v_writelane_b32 v252, s7, 50
	s_ashr_i32 s25, s24, 31
	s_lshr_b32 s8, s11, 2
	v_writelane_b32 v252, s10, 51
	s_mul_i32 s7, s87, s86
	s_nop 0
	v_writelane_b32 v252, s11, 52
	s_lshl_b64 s[10:11], s[24:25], 20
	s_add_u32 s10, s90, s10
	s_addc_u32 s11, s91, s11
	s_add_u32 s24, s10, 0x80000
	v_writelane_b32 v252, s10, 53
	s_addc_u32 s25, s11, 0
	s_ashr_i32 s61, s60, 31
	v_writelane_b32 v252, s11, 54
	s_bfe_i64 s[10:11], s[20:21], 0x100000
	v_writelane_b32 v252, s24, 55
	s_lshl_b64 s[10:11], s[10:11], 20
	s_lshl_b64 s[20:21], s[60:61], 20
	v_writelane_b32 v252, s25, 56
	s_add_u32 s24, s28, s10
	v_writelane_b32 v252, s28, 57
	s_addc_u32 s25, s29, s11
	s_nop 0
	v_writelane_b32 v252, s29, 58
	s_add_u32 s28, s24, 0x80000
	s_addc_u32 s29, s25, 0
	v_writelane_b32 v252, s28, 59
	s_nop 1
	v_writelane_b32 v252, s29, 60
	s_add_u32 s28, s42, s20
	s_addc_u32 s29, s43, s21
	s_add_u32 s34, s28, 0x80000
	v_writelane_b32 v252, s28, 61
	s_addc_u32 s35, s29, 0
	s_nop 0
	v_writelane_b32 v252, s29, 62
	v_writelane_b32 v252, s34, 63
	s_add_u32 s28, s24, 0x80080
	s_nop 0
	v_writelane_b32 v253, s35, 0
	v_writelane_b32 v253, s24, 1
	s_addc_u32 s29, s25, 0
	s_add_u32 s10, s30, s10
	v_writelane_b32 v253, s25, 2
	v_writelane_b32 v253, s28, 3
	s_movk_i32 s35, 0x5000
	s_nop 0
	v_writelane_b32 v253, s29, 4
	v_writelane_b32 v253, s30, 5
	s_addc_u32 s11, s31, s11
	s_add_u32 s24, s10, 0x80000
	v_writelane_b32 v253, s31, 6
	s_addc_u32 s25, s11, 0
	v_writelane_b32 v253, s24, 7
	s_add_u32 s20, s62, s20
	s_addc_u32 s21, s63, s21
	v_writelane_b32 v253, s25, 8
	s_add_u32 s24, s20, 0x80000
	v_writelane_b32 v253, s20, 9
	s_addc_u32 s25, s21, 0
	s_nop 0
	v_writelane_b32 v253, s21, 10
	v_writelane_b32 v253, s24, 11
	s_add_u32 s20, s10, 0x80080
	s_nop 0
	v_writelane_b32 v253, s25, 12
	v_writelane_b32 v253, s10, 13
	s_addc_u32 s21, s11, 0
	s_ashr_i32 s23, s22, 31
	v_writelane_b32 v253, s11, 14
	v_writelane_b32 v253, s20, 15
	s_mov_b32 s10, s22
	s_bfe_i64 s[8:9], s[8:9], 0x100000
	v_writelane_b32 v253, s21, 16
	v_writelane_b32 v253, s10, 17
	s_lshl_b64 s[8:9], s[8:9], 20
	s_mov_b32 s24, 0x3db504f3
	v_writelane_b32 v253, s11, 18
	s_lshl_b64 s[10:11], s[22:23], 20
	s_add_u32 s20, s40, s8
	v_writelane_b32 v253, s40, 19
	s_addc_u32 s21, s41, s9
	s_add_u32 s8, s20, 0x80000
	v_writelane_b32 v253, s41, 20
	s_addc_u32 s9, s21, 0
	v_writelane_b32 v253, s8, 21
	s_add_u32 s10, s90, s10
	s_addc_u32 s11, s91, s11
	v_writelane_b32 v253, s9, 22
	s_load_dword s8, s[0:1], 0x100
	s_waitcnt lgkmcnt(0)
; #define LAS __attribute__((address_space(3)))
; __global__ void __launch_bounds__(512, 2) mega_fwd(Args a) {
;     extern __shared__ __attribute__((aligned(16))) unsigned char lds[];
;     cg::grid_group grid = cg::this_grid();
;     constexpr int G = 256;
;     unsigned char* ws = a.ws;
;     LAS unsigned char* ldsl = (LAS unsigned char*)lds;
;     unsigned long long* rssb = (unsigned long long*)(ws + WS_RSS);
;     volatile LAS unsigned* bst = (volatile LAS unsigned*)(ldsl + (LDS_BYTES - 64));
;     if (threadIdx.x < 2) bst[threadIdx.x] = 0u;
;     __syncthreads();
;     XcdBarrier bar = xcd_barrier_post((unsigned*)(ws + WS_BAR), bst);
;     ...
;     if (a.ph_lo < 0) grid.sync();
;     ...
;     for (int ph = a.ph_lo; ph < a.ph_hi; ++ph) {
	s_mul_i32 s7, s7, s8
	v_writelane_b32 v253, s7, 23
	s_add_u32 s8, s10, 0x80000
	v_writelane_b32 v253, s10, 24
	s_addc_u32 s9, s11, 0
	s_mul_hi_i32 s7, s60, 0x2c0000
	v_writelane_b32 v253, s11, 25
	v_writelane_b32 v253, s8, 26
	s_nop 1
	v_writelane_b32 v253, s9, 27
	s_add_u32 s8, s20, 0x80080
	v_writelane_b32 v253, s20, 28
	s_addc_u32 s9, s21, 0
	s_nop 0
	v_writelane_b32 v253, s21, 29
	v_writelane_b32 v253, s8, 30
	s_nop 1
	v_writelane_b32 v253, s9, 31
	s_mov_b32 s8, s60
	v_writelane_b32 v253, s8, 32
	s_nop 1
	v_writelane_b32 v253, s9, 33
	s_mul_i32 s8, s60, 0x2c0000
	s_add_u32 s8, s66, s8
	s_addc_u32 s9, s67, s7
	s_add_u32 s10, s8, 0x160000
	v_writelane_b32 v253, s8, 34
	s_addc_u32 s11, s9, 0
	s_mov_b64 s[60:61], s[56:57]
	v_writelane_b32 v253, s9, 35
	v_writelane_b32 v253, s10, 36
	s_add_u32 s8, s66, s4
	s_addc_u32 s9, s67, 0
	v_writelane_b32 v253, s11, 37
	v_writelane_b32 v253, s8, 38
	s_add_u32 s4, s66, s5
	s_addc_u32 s5, s67, 0
	v_writelane_b32 v253, s9, 39
	v_writelane_b32 v253, s4, 40
	s_nop 1
	v_writelane_b32 v253, s5, 41
	s_add_u32 s4, s66, s6
	v_writelane_b32 v253, s66, 42
	s_addc_u32 s5, s67, 0
	s_nop 0
	v_writelane_b32 v253, s67, 43
	v_writelane_b32 v253, s4, 44
	s_mov_b32 s66, 0x1ffff
	s_nop 0
	v_writelane_b32 v253, s5, 45
	s_lshl_b64 s[4:5], s[2:3], 16
	s_add_u32 s6, s82, s4
	s_addc_u32 s7, s83, s5
	s_add_u32 s4, s6, 0x1a801080
	s_addc_u32 s5, s7, 0
	v_writelane_b32 v253, s4, 46
	s_lshl_b32 s8, s2, 2
	s_nop 0
	v_writelane_b32 v253, s5, 47
	s_lshl_b64 s[4:5], s[68:69], 19
	v_writelane_b32 v253, s8, 48
	s_lshl_b64 s[8:9], s[2:3], 8
	s_add_u32 s4, s82, s4
	s_addc_u32 s5, s83, s5
	v_writelane_b32 v253, s8, 49
	s_add_u32 s4, s4, 0x34800080
	s_addc_u32 s5, s5, 0
	v_writelane_b32 v253, s9, 50
	v_writelane_b32 v253, s4, 51
	s_load_dwordx16 s[8:23], s[0:1], 0x80
	s_mov_b64 s[68:69], 0x400
	v_writelane_b32 v253, s5, 52
	s_lshl_b64 s[4:5], s[72:73], 19
	s_add_u32 s4, s82, s4
	s_addc_u32 s5, s83, s5
	s_add_u32 s4, s4, 0x34800080
	s_addc_u32 s5, s5, 0
	v_writelane_b32 v253, s4, 53
	s_mov_b64 s[72:73], s[42:43]
	s_nop 0
	v_writelane_b32 v253, s5, 54
	s_lshl_b32 s4, s2, 11
	v_writelane_b32 v253, s4, 55
	s_add_i32 s4, s2, 0x100
	v_writelane_b32 v253, s4, 56
	s_lshl_b64 s[4:5], s[2:3], 9
	s_add_u32 s4, s82, s4
	s_addc_u32 s5, s83, s5
	s_add_u32 s4, s4, 0x300000
	s_addc_u32 s5, s5, 0
	v_writelane_b32 v253, s4, 57
	s_nop 1
	v_writelane_b32 v253, s5, 58
	s_add_u32 s4, s6, 0x1a800080
	s_addc_u32 s5, s7, 0
	v_writelane_b32 v253, s4, 59
	s_nop 1
	v_writelane_b32 v253, s5, 60
	s_add_u32 s4, s82, 0x34800100
	s_addc_u32 s5, s83, 0
	v_writelane_b32 v253, s4, 61
	s_nop 1
	v_writelane_b32 v253, s5, 62
	s_lshl_b32 s4, s2, 12
	v_writelane_b32 v253, s4, 63
	s_lshl_b32 s4, s2, 10
	v_writelane_b32 v254, s4, 0
	s_lshl_b64 s[4:5], s[36:37], 2
	s_waitcnt lgkmcnt(0)
	s_add_u32 s4, s18, s4
	v_writelane_b32 v254, s4, 1
	v_writelane_b32 v254, s8, 2
	s_addc_u32 s4, s19, s5
	s_movk_i32 s37, 0x141
	v_writelane_b32 v254, s9, 3
	v_writelane_b32 v254, s10, 4
	v_writelane_b32 v254, s11, 5
	v_writelane_b32 v254, s12, 6
	v_writelane_b32 v254, s13, 7
	v_writelane_b32 v254, s14, 8
	v_writelane_b32 v254, s15, 9
	v_writelane_b32 v254, s16, 10
	v_writelane_b32 v254, s17, 11
	v_writelane_b32 v254, s18, 12
	v_writelane_b32 v254, s19, 13
	v_writelane_b32 v254, s20, 14
	v_writelane_b32 v254, s21, 15
	v_writelane_b32 v254, s22, 16
	v_writelane_b32 v254, s23, 17
	v_writelane_b32 v254, s4, 18
	s_add_u32 s4, s58, 8
	v_writelane_b32 v254, s4, 19
	s_addc_u32 s4, s59, 0
	v_writelane_b32 v254, s4, 20
	s_load_dwordx16 s[4:19], s[0:1], 0x40
	s_mov_b64 s[58:59], s[54:55]
	s_mov_b64 s[56:57], s[52:53]
	s_mov_b64 s[54:55], s[50:51]
	s_mov_b64 s[52:53], s[48:49]
	s_waitcnt lgkmcnt(0)
	s_add_u32 s0, s4, 8
	v_writelane_b32 v254, s0, 21
	v_writelane_b32 v254, s4, 22
	s_addc_u32 s0, s5, 0
	s_mov_b64 s[50:51], s[46:47]
	v_writelane_b32 v254, s5, 23
	v_writelane_b32 v254, s6, 24
	v_writelane_b32 v254, s7, 25
	v_writelane_b32 v254, s8, 26
	v_writelane_b32 v254, s9, 27
	v_writelane_b32 v254, s10, 28
	v_writelane_b32 v254, s11, 29
	v_writelane_b32 v254, s12, 30
	v_writelane_b32 v254, s13, 31
	v_writelane_b32 v254, s14, 32
	v_writelane_b32 v254, s15, 33
	v_writelane_b32 v254, s16, 34
	v_writelane_b32 v254, s17, 35
	v_writelane_b32 v254, s18, 36
	v_writelane_b32 v254, s19, 37
	v_writelane_b32 v254, s0, 38
	s_mov_b32 s0, s36
	v_writelane_b32 v254, s0, 39
	s_mov_b64 s[48:49], s[44:45]
	s_add_i32 s96, s36, 0xfffff800
	v_writelane_b32 v254, s1, 40
	v_writelane_b32 v254, s48, 41
	s_add_u32 s0, s44, 0x1000
	s_addc_u32 s1, s45, 0
	v_writelane_b32 v254, s49, 42
	v_writelane_b32 v254, s50, 43
	v_writelane_b32 v254, s51, 44
	v_writelane_b32 v254, s52, 45
	v_writelane_b32 v254, s53, 46
	v_writelane_b32 v254, s54, 47
	v_writelane_b32 v254, s55, 48
	v_writelane_b32 v254, s56, 49
	v_writelane_b32 v254, s57, 50
	v_writelane_b32 v254, s58, 51
	v_writelane_b32 v254, s59, 52
	v_writelane_b32 v254, s60, 53
	v_writelane_b32 v254, s61, 54
	v_writelane_b32 v254, s62, 55
	v_writelane_b32 v254, s63, 56
	v_writelane_b32 v254, s0, 57
	s_mov_b64 s[58:59], s[62:63]
	s_mov_b32 s10, 0xffff0000
	v_writelane_b32 v254, s1, 58
	v_writelane_b32 v254, s38, 59
	s_add_i32 s0, s38, 0xfffe0000
	v_writelane_b32 v254, s0, 60
	s_add_u32 s0, s82, 0x20000
	s_addc_u32 s1, s83, 0
	v_writelane_b32 v254, s0, 61
	s_mov_b32 s7, 0x800000
	s_mov_b32 s11, 0xe800000
	v_writelane_b32 v254, s1, 62
	s_add_u32 s0, s82, 0xc0000
	s_addc_u32 s1, s83, 0
	v_writelane_b32 v254, s0, 63
	s_movk_i32 s6, 0x2c00
	s_mov_b32 s5, s84
	v_writelane_b32 v248, s1, 0
	s_add_u32 s0, s80, 0x1000
	s_addc_u32 s1, s81, 0
	v_writelane_b32 v248, s0, 1
	s_mov_b64 s[14:15], 0x1000
	s_mov_b64 s[12:13], 0x80
	v_writelane_b32 v248, s1, 2
	s_add_i32 s0, 0, 0x23fc0
	v_writelane_b32 v248, s0, 3
	s_add_i32 s0, 0, 0x23fc4
	v_writelane_b32 v248, s0, 4
	s_add_i32 s0, 0, 0x10800
	v_writelane_b32 v248, s0, 5
	s_add_i32 s0, 0, 0x14c00
	v_writelane_b32 v248, s0, 6
	s_add_i32 s0, 0, 0x1dc00
	v_writelane_b32 v248, s0, 7
	s_mov_b32 s1, 0xbf8c71c7
	v_writelane_b32 v248, s0, 8
	s_mov_b32 s9, 0x3fd55555
	s_nop 0
	v_writelane_b32 v248, s1, 9
	s_mov_b32 s1, 0xbfa99999
	v_writelane_b32 v248, s0, 10
	s_nop 1
	v_writelane_b32 v248, s1, 11
	s_mov_b32 s1, 0xbfc55555
	v_writelane_b32 v248, s0, 12
	s_nop 1
	v_writelane_b32 v248, s1, 13
	s_mov_b32 s1, 0xbf924924
	v_writelane_b32 v248, s0, 14
	s_nop 1
	v_writelane_b32 v248, s1, 15
	s_mov_b32 s1, 0xbfa11111
	v_writelane_b32 v248, s0, 16
	s_nop 1
	v_writelane_b32 v248, s1, 17
	s_mov_b32 s1, 0xbfb55555
	v_writelane_b32 v248, s0, 18
	s_nop 1
	v_writelane_b32 v248, s1, 19
	s_mov_b32 s1, 0x3fc99999
	v_writelane_b32 v248, s0, 20
	s_nop 1
	v_writelane_b32 v248, s1, 21
	v_writelane_b32 v248, s72, 22
	s_nop 1
	v_writelane_b32 v248, s73, 23
	s_mov_b32 s100, 0
	s_branch .LBB0_21

; __global__ void __launch_bounds__(512, 2) mega_fwd(Args a) {
;     ...
;     for (int ph = a.ph_lo; ph < a.ph_hi; ++ph) {
;         if (ph != a.ph_lo) {
;             xcd_barrier(bar);
.LBB0_20:
	s_mov_b32 s100, 0
	s_add_i32 s5, s5, 1
	s_cmp_ge_i32 s5, s85
	s_cbranch_scc0 .LBB0_21
	s_getpc_b64 s[98:99]

; __global__ void __launch_bounds__(512, 2) mega_fwd(Args a) {
;     ...
;         if (ph == N_PHASES - 1) { phase_final(a, G); continue; }
;         const int l = ph / PH_PER_LAYER, k = ph % PH_PER_LAYER;
;     ...
;         for (int rep = 0; rep < ((k == PROBE_K) ? 2 : 1); ++rep) {
;         if (rep) xcd_barrier(bar);
;     ...
;         if (k == 0) {
;     ...
;             phase_prep(a, l, lds, G);
.LBB0_77:
	s_mul_hi_i32 s0, s5, 0x2aaaaaab
	s_mov_b64 s[16:17], 0
	s_lshr_b32 s1, s0, 31
	s_ashr_i32 s0, s0, 1
	v_writelane_b32 v248, s16, 24
	s_add_i32 s86, s0, s1
	s_mul_i32 s0, s86, 12
	v_writelane_b32 v248, s17, 25
	s_mov_b64 s[16:17], 0
	v_writelane_b32 v248, s16, 26
	s_sub_i32 s67, s5, s0
	s_cmp_lg_u32 s67, 0
	s_cbranch_scc1 .Lov_skip
	s_cmp_lg_u32 s100, 0
	s_cbranch_scc1 .Lov_skip
	s_bitcmp1_b32 s2, 3
	s_cbranch_scc0 .Lov_skip
	s_mov_b32 s100, 1
.Lov_skip:
	s_mov_b64 s[0:1], -1
	v_writelane_b32 v248, s17, 27
	s_mov_b64 s[16:17], 0
	s_cmp_lt_i32 s67, 6
	v_writelane_b32 v248, s16, 28
	s_nop 1
	v_writelane_b32 v248, s17, 29
	s_cbranch_scc1 .LBB0_317
	s_cmp_gt_i32 s67, 8
	s_cbranch_scc0 .LBB0_82
	s_cmp_gt_i32 s67, 9
	s_cbranch_scc0 .LBB0_83
	s_mov_b64 s[16:17], -1
	v_writelane_b32 v248, s16, 26
	s_mov_b64 s[0:1], 0
	s_cmp_gt_i32 s67, 10
	v_writelane_b32 v248, s17, 27
	s_mov_b64 s[16:17], 0
	s_cbranch_scc0 .LBB0_84
	v_writelane_b32 v248, s16, 26
	s_cmp_eq_u32 s67, 11
	s_nop 0
	v_writelane_b32 v248, s17, 27
	s_cselect_b64 s[16:17], -1, 0
	s_branch .LBB0_84

; __device__ __forceinline__ void gla_kv_load(const Args& a, int unit, int tid, KvIn& r) {
;     const int lane = tid & 63, wave = tid >> 6, r16 = lane & 15, quad = lane >> 4;
;     const int bh = unit >> 6, n = unit & 63, b = bh >> 2, h = bh & 3, t0 = b * SEQ + n * 64;
;     const bf16_t* Z = (const bf16_t*)(a.ws + WS_Z); const float* GLR = (const float*)(a.ws + WS_GLR);
; #pragma unroll
;     for (int jb = 0; jb < 4; ++jb) {
;         if (quad < 2) { const float* gp = GLR + (size_t)(t0 + jb * 16 + r16) * 16 + quad * 8; r.g[jb][0] = *(const f32x4*)gp; r.g[jb][1] = *(const f32x4*)(gp + 4); }
;         else { r.g[jb][0] = (f32x4){0.f, 0.f, 0.f, 0.f}; r.g[jb][1] = (f32x4){0.f, 0.f, 0.f, 0.f}; }
; #pragma unroll
;         for (int i = 0; i < 4; ++i) r.k[jb * 4 + i] = Z[(size_t)(t0 + jb * 16 + quad * 4 + i) * ZW + ZC_K + h * 128 + wave * 16 + r16];
;     }
; #pragma unroll
;     for (int i = 0; i < 4; ++i) r.v[i] = *(const u32x4*)(Z + (size_t)(t0 + 4 * (tid >> 5) + i) * ZW + ZC_V + h * 256 + (tid & 31) * 8);
; }
; __device__ __forceinline__ void gla_kv_unit(const Args& a, unsigned char* lds, int unit, int next, int tid, KvIn& in, const bf16x8 wfrag, float bias) {
;     const int lane = tid & 63, wave = tid >> 6, r16 = lane & 15, quad = lane >> 4;
;     const int bh = unit >> 6, n = unit & 63, b = bh >> 2, h = bh & 3, t0 = b * SEQ + n * 64;
;     bf16_t* KV = (bf16_t*)(a.ws + WS_KV); float* DEC = (float*)(a.ws + WS_DEC); float* BCG = (float*)(a.ws + WS_BCG);
;     bf16_t* KTl = (bf16_t*)(lds + OFF_QP); bf16_t* VT = (bf16_t*)(lds + OFF_VT);
;     u32x4 vreg[4];
; #pragma unroll
;     for (int i = 0; i < 4; ++i) vreg[i] = in.v[i];
;     const int d = wave * 16 + r16;
;     float bc[4][4]; float carry = 0.f;
; #pragma unroll
;     for (int jb = 0; jb < 4; ++jb) {
;         bf16x8 af; { const f32x4 g0 = in.g[jb][0], g1 = in.g[jb][1]; u32x4 pw; pw.x = pk2(g0[0], g0[1]); pw.y = pk2(g0[2], g0[3]); pw.z = pk2(g1[0], g1[1]); pw.w = pk2(g1[2], g1[3]); af = __builtin_bit_cast(bf16x8, pw); }
;         const f32x4 z = mfma16(af, wfrag, (f32x4){0.f, 0.f, 0.f, 0.f});
;         float la[4];
; #pragma unroll
;         for (int i = 0; i < 4; ++i) { const float zz = z[i] + bias; la[i] = (fminf(zz, 0.f) - __logf(1.f + __expf(-fabsf(zz)))) * (1.f / 16.f); }
;         la[1] += la[0]; la[2] += la[1]; la[3] += la[2];
;         const float s = la[3];
.LBB0_341:
	s_or_b64 exec, exec, s[0:1]
	v_readlane_b32 s0, v251, 47
	v_readlane_b32 s1, v251, 48
	s_andn2_b64 vcc, exec, s[0:1]
	s_cbranch_vccnz .LBB0_356
	v_ashrrev_i32_e32 v87, 3, v52
	v_and_b32_e32 v90, -4, v87
	v_readlane_b32 s0, v250, 60
	v_lshlrev_b32_e32 v98, 3, v52
	v_and_b32_e32 v68, 0xf8, v98
	v_add_u32_e32 v55, s0, v90
	v_readlane_b32 s0, v253, 44
	v_readlane_b32 s1, v253, 45
	s_waitcnt vmcnt(10)
	v_and_b32_e32 v77, 0xffff, v38
	v_and_b32_e32 v78, 0xffff, v37
	v_or_b32_e32 v38, 3, v55
	v_mov_b64_e32 v[36:37], s[0:1]
	s_waitcnt vmcnt(4)
	v_and_b32_e32 v75, 0xffff, v42
	v_and_b32_e32 v76, 0xffff, v41
	v_and_b32_e32 v79, 0xffff, v40
	v_and_b32_e32 v80, 0xffff, v39
	v_mad_i64_i32 v[38:39], s[0:1], v38, s35, v[36:37]
	v_lshlrev_b32_e32 v40, 1, v68
	v_mov_b32_e32 v41, v137
	v_or_b32_e32 v42, 2, v55
	v_and_b32_e32 v74, 0xffff, v43
	v_lshl_add_u64 v[38:39], v[38:39], 0, v[40:41]
	v_mad_i64_i32 v[42:43], s[0:1], v42, s35, v[36:37]
	s_waitcnt vmcnt(2)
	v_and_b32_e32 v69, 0xffff, v46
	v_and_b32_e32 v70, 0xffff, v45
	s_waitcnt vmcnt(0)
	v_and_b32_e32 v71, 0xffff, v48
	v_and_b32_e32 v72, 0xffff, v47
	v_and_b32_e32 v73, 0xffff, v44
	v_lshl_add_u64 v[42:43], v[42:43], 0, v[40:41]
	global_load_dwordx4 v[44:47], v[38:39], off offset:3072
	global_load_dwordx4 v[48:51], v[42:43], off offset:3072
	v_or_b32_e32 v38, 1, v55
	v_mad_i64_i32 v[38:39], s[0:1], v38, s35, v[36:37]
	v_mad_i64_i32 v[36:37], s[0:1], v55, s35, v[36:37]
	v_readlane_b32 s0, v250, 56
	v_readlane_b32 s1, v250, 57
	v_or_b32_e32 v55, 51, v54
	v_lshl_add_u64 v[38:39], v[38:39], 0, v[40:41]
	v_mov_b64_e32 v[60:61], s[0:1]
	v_mad_i64_i32 v[62:63], s[0:1], v55, s35, v[60:61]
	v_or_b32_e32 v55, 50, v54
	v_mad_i64_i32 v[64:65], s[0:1], v55, s35, v[60:61]
	v_or_b32_e32 v55, 49, v54
	v_or_b32_e32 v54, 48, v54
	v_lshl_add_u64 v[62:63], v[62:63], 0, v[58:59]
	v_mad_i64_i32 v[66:67], s[0:1], v55, s35, v[60:61]
	v_mad_i64_i32 v[54:55], s[0:1], v54, s35, v[60:61]
	v_lshl_add_u64 v[40:41], v[36:37], 0, v[40:41]
	v_lshl_add_u64 v[62:63], v[62:63], 0, v[136:137]
	v_lshl_add_u64 v[64:65], v[64:65], 0, v[58:59]
	v_lshl_add_u64 v[66:67], v[66:67], 0, v[58:59]
	v_lshl_add_u64 v[54:55], v[54:55], 0, v[58:59]
	global_load_dwordx4 v[36:39], v[38:39], off offset:3072
	s_nop 0
	global_load_dwordx4 v[40:43], v[40:41], off offset:3072
	v_lshl_add_u64 v[64:65], v[64:65], 0, v[136:137]
	v_lshl_add_u64 v[66:67], v[66:67], 0, v[136:137]
	v_lshl_add_u64 v[54:55], v[54:55], 0, v[136:137]
	global_load_ushort v83, v[62:63], off offset:2048
	global_load_ushort v84, v[64:65], off offset:2048
	global_load_ushort v81, v[66:67], off offset:2048
	global_load_ushort v82, v[54:55], off offset:2048
	v_add_u32_e32 v54, -16, v177
	v_and_b32_e32 v55, 64, v177
	v_cmp_lt_i32_e32 vcc, v54, v55
	v_lshlrev_b32_e32 v86, 3, v53
	v_cmp_lt_u32_e64 s[40:41], 1, v53
	v_cndmask_b32_e32 v54, v54, v177, vcc
	v_lshlrev_b32_e32 v91, 2, v54
	v_subrev_u32_e32 v54, 32, v177
	v_cmp_lt_i32_e64 s[0:1], v54, v55
	v_cmp_eq_u32_e32 vcc, 0, v53
	v_or_b32_e32 v53, 48, v88
	v_cndmask_b32_e64 v54, v54, v177, s[0:1]
	v_ashrrev_i32_e32 v64, 6, v52
	v_lshlrev_b32_e32 v92, 2, v54
	v_or_b32_e32 v54, v55, v53
	v_lshlrev_b32_e32 v93, 2, v54
	v_lshl_or_b32 v54, v64, 4, v88
	v_ashrrev_i32_e32 v55, 31, v54
	v_readlane_b32 s0, v250, 61
	v_lshlrev_b64 v[62:63], 2, v[54:55]
	v_readlane_b32 s1, v250, 62
	v_and_b32_e32 v55, 4, v89
	v_lshlrev_b32_e32 v55, 1, v55
	v_lshl_add_u64 v[60:61], s[0:1], 0, v[62:63]
	s_movk_i32 s1, 0x90
	v_mul_lo_u32 v65, v54, s1
	v_add3_u32 v55, 0, v55, v65
	v_bitop3_b32 v65, v89, 56, v54 bitop3:0x48
	v_lshl_add_u32 v94, v65, 1, v55
	v_or_b32_e32 v65, 16, v89
	v_bitop3_b32 v65, v65, 56, v54 bitop3:0x48
	v_lshl_add_u32 v95, v65, 1, v55
	v_or_b32_e32 v65, 32, v89
	v_bitop3_b32 v65, v65, 56, v54 bitop3:0x48
	v_lshl_add_u32 v96, v65, 1, v55
	v_or_b32_e32 v65, 48, v89
	v_bitop3_b32 v54, v65, 56, v54 bitop3:0x48
	v_lshl_add_u32 v97, v54, 1, v55
	v_and_b32_e32 v54, 56, v98
	s_mov_b32 s0, 0x7ffffff8
	v_bitop3_b32 v54, v87, v54, s0 bitop3:0x6c
	v_lshlrev_b32_e32 v55, 1, v87
	v_and_b32_e32 v55, 8, v55
	v_lshlrev_b32_e32 v54, 1, v54
	v_readlane_b32 s0, v248, 6
	v_bitop3_b32 v53, v53, v86, 56 bitop3:0x6c
	v_lshl_add_u32 v104, v53, 1, 0
	v_add3_u32 v87, s0, v55, v54
	v_lshl_or_b32 v54, v64, 5, v88
	v_bitop3_b32 v64, v54, v86, 40 bitop3:0x6c
	v_lshl_add_u32 v99, v64, 1, s0
	v_or_b32_e32 v64, 16, v54
	v_bitop3_b32 v65, v64, v86, 56 bitop3:0x6c
	v_lshl_add_u32 v100, v65, 1, s0
	v_bitop3_b32 v65, v86, v52, 8 bitop3:0x78
	v_lshl_add_u32 v101, v65, 1, 0
	v_or_b32_e32 v65, 16, v88
	v_or_b32_e32 v53, 32, v86
	v_and_b32_e32 v55, 8, v52
	v_bitop3_b32 v65, v65, v86, 24 bitop3:0x6c
	v_bitop3_b32 v105, v54, v53, 40 bitop3:0x6c
	v_bitop3_b32 v53, v64, v53, 56 bitop3:0x6c
	v_bitop3_b32 v66, v88, 24, 16 bitop3:0xc8
	v_lshl_add_u32 v102, v65, 1, 0
	v_or_b32_e32 v65, 32, v88
	v_lshl_add_u32 v107, v53, 1, s0
	v_bitop3_b32 v53, v86, v55, 32 bitop3:0x36
	v_bitop3_b32 v67, v88, 40, 32 bitop3:0xc8
	v_bitop3_b32 v65, v65, v86, 40 bitop3:0x6c
	v_lshl_add_u32 v108, v53, 1, 0
	v_bitop3_b32 v53, v86, v66, 32 bitop3:0x36
	v_mul_lo_u32 v106, v54, s1
	v_lshl_add_u32 v103, v65, 1, 0
	v_bitop3_b32 v65, v88, 56, 48 bitop3:0xc8
	v_lshl_add_u32 v105, v105, 1, s0
	v_lshl_add_u32 v109, v53, 1, 0
	v_bitop3_b32 v53, v86, v67, 32 bitop3:0x36
	v_readlane_b32 s0, v253, 57
	v_lshl_add_u32 v111, v53, 1, 0
	v_bitop3_b32 v53, v86, v65, 32 bitop3:0x36
	v_readlane_b32 s1, v253, 58
	v_ashrrev_i32_e32 v65, 31, v64
	v_lshrrev_b32_e32 v52, 1, v52
	v_ashrrev_i32_e32 v55, 31, v54
	v_lshl_add_u32 v86, v53, 1, 0
	v_lshl_add_u64 v[62:63], s[0:1], 0, v[62:63]
	v_lshlrev_b64 v[64:65], 8, v[64:65]
	v_and_b32_e32 v66, 24, v52
	v_readlane_b32 s0, v253, 59
	v_lshlrev_b64 v[52:53], 8, v[54:55]
	v_mul_u32_u24_e32 v98, 0x90, v68
	v_mul_u32_u24_e32 v110, 0x90, v88
	v_or_b32_e32 v64, v64, v66
	v_readlane_b32 s1, v253, 60
	v_or_b32_e32 v52, v52, v66
	v_add_u32_e32 v98, v87, v98
	v_lshl_add_u64 v[64:65], s[0:1], 0, v[64:65]
	v_lshl_add_u64 v[66:67], s[0:1], 0, v[52:53]
	v_lshlrev_b32_e32 v68, 1, v68
	v_add_u32_e32 v99, v99, v106
	v_add_u32_e32 v100, v100, v106
	v_add_u32_e32 v101, v101, v110
	v_add_u32_e32 v102, v102, v110
	v_add_u32_e32 v103, v103, v110
	v_add_u32_e32 v104, v104, v110
	v_add_u32_e32 v105, v105, v106
	v_add_u32_e32 v106, v107, v106
	v_add_u32_e32 v107, v108, v110
	v_add_u32_e32 v108, v109, v110
	v_add_u32_e32 v109, v111, v110
	v_add_u32_e32 v110, v86, v110
	v_readlane_b32 s28, v250, 34
	v_readlane_b32 s30, v250, 51
	v_readlane_b32 s34, v250, 50
	v_readlane_b32 s36, v253, 56
	s_branch .LBB0_345
; __device__ __forceinline__ void gla_kv_load(const Args& a, int unit, int tid, KvIn& r) {
;     const int lane = tid & 63, wave = tid >> 6, r16 = lane & 15, quad = lane >> 4;
;     const int bh = unit >> 6, n = unit & 63, b = bh >> 2, h = bh & 3, t0 = b * SEQ + n * 64;
;     const bf16_t* Z = (const bf16_t*)(a.ws + WS_Z); const float* GLR = (const float*)(a.ws + WS_GLR);
; #pragma unroll
;     for (int jb = 0; jb < 4; ++jb) {
;         if (quad < 2) { const float* gp = GLR + (size_t)(t0 + jb * 16 + r16) * 16 + quad * 8; r.g[jb][0] = *(const f32x4*)gp; r.g[jb][1] = *(const f32x4*)(gp + 4); }
;         else { r.g[jb][0] = (f32x4){0.f, 0.f, 0.f, 0.f}; r.g[jb][1] = (f32x4){0.f, 0.f, 0.f, 0.f}; }
; #pragma unroll
;         for (int i = 0; i < 4; ++i) r.k[jb * 4 + i] = Z[(size_t)(t0 + jb * 16 + quad * 4 + i) * ZW + ZC_K + h * 128 + wave * 16 + r16];
;     }
; #pragma unroll
;     for (int i = 0; i < 4; ++i) r.v[i] = *(const u32x4*)(Z + (size_t)(t0 + 4 * (tid >> 5) + i) * ZW + ZC_V + h * 256 + (tid & 31) * 8);
; }
.Lov_tramp:
	s_branch .LBB0_77
.LBB0_343:
	s_or_b64 exec, exec, s[22:23]
	v_or_b32_e32 v36, 48, v37
	v_mov_b64_e32 v[38:39], s[0:1]
	v_mad_u64_u32 v[40:41], s[0:1], v36, s35, v[38:39]
	v_or_b32_e32 v36, 49, v37
	v_mad_u64_u32 v[42:43], s[0:1], v36, s35, v[38:39]
	v_or_b32_e32 v36, 50, v37
	v_mad_u64_u32 v[44:45], s[0:1], v36, s35, v[38:39]
	v_or_b32_e32 v36, 51, v37
	v_mad_u64_u32 v[36:37], s[0:1], v36, s35, v[38:39]
	v_lshl_add_u64 v[40:41], v[40:41], 0, v[58:59]
	v_lshl_add_u64 v[44:45], v[44:45], 0, v[58:59]
	v_readlane_b32 s0, v253, 42
	v_lshl_add_u64 v[40:41], v[40:41], 0, v[136:137]
	v_lshl_add_u64 v[42:43], v[42:43], 0, v[58:59]
	v_lshl_add_u64 v[44:45], v[44:45], 0, v[136:137]
	v_lshl_add_u64 v[36:37], v[36:37], 0, v[58:59]
	v_readlane_b32 s1, v253, 43
	v_lshl_add_u64 v[42:43], v[42:43], 0, v[136:137]
	v_lshl_add_u64 v[36:37], v[36:37], 0, v[136:137]
	global_load_ushort v82, v[40:41], off offset:2048
	global_load_ushort v81, v[42:43], off offset:2048
	global_load_ushort v84, v[44:45], off offset:2048
	global_load_ushort v83, v[36:37], off offset:2048
	v_add_u32_e32 v48, s20, v90
	v_mov_b64_e32 v[44:45], s[0:1]
	v_mad_i64_i32 v[36:37], s[0:1], v48, s35, v[44:45]
	v_or_b32_e32 v38, 1, v48
	v_or_b32_e32 v46, 2, v48
	v_or_b32_e32 v48, 3, v48
	s_lshl_b32 s88, s27, 9
	v_mad_i64_i32 v[38:39], s[0:1], v38, s35, v[44:45]
	v_mad_i64_i32 v[46:47], s[0:1], v46, s35, v[44:45]
	v_mad_i64_i32 v[44:45], s[0:1], v48, s35, v[44:45]
	v_lshl_add_u64 v[36:37], v[36:37], 0, s[88:89]
	v_mov_b32_e32 v69, v137
	v_lshl_add_u64 v[38:39], v[38:39], 0, s[88:89]
	v_lshl_add_u64 v[46:47], v[46:47], 0, s[88:89]
	v_lshl_add_u64 v[44:45], v[44:45], 0, s[88:89]
	v_lshl_add_u64 v[36:37], v[36:37], 0, v[68:69]
	v_lshl_add_u64 v[38:39], v[38:39], 0, v[68:69]
	v_lshl_add_u64 v[46:47], v[46:47], 0, v[68:69]
	v_lshl_add_u64 v[44:45], v[44:45], 0, v[68:69]
	global_load_dwordx4 v[40:43], v[36:37], off offset:3072
	s_nop 0
	global_load_dwordx4 v[36:39], v[38:39], off offset:3072
	s_nop 0
	global_load_dwordx4 v[48:51], v[46:47], off offset:3072
	s_nop 0
	global_load_dwordx4 v[44:47], v[44:45], off offset:3072
	s_waitcnt vmcnt(10)
	v_and_b32_e32 v69, 0xffff, v71
	v_and_b32_e32 v70, 0xffff, v70
	s_waitcnt vmcnt(8)
	v_and_b32_e32 v71, 0xffff, v77
	v_and_b32_e32 v72, 0xffff, v72
	v_and_b32_e32 v73, 0xffff, v73
	v_and_b32_e32 v74, 0xffff, v74
	v_and_b32_e32 v75, 0xffff, v75
	v_and_b32_e32 v76, 0xffff, v76
	v_and_b32_e32 v77, 0xffff, v53
	v_and_b32_e32 v78, 0xffff, v52
	v_and_b32_e32 v79, 0xffff, v55
	v_and_b32_e32 v80, 0xffff, v54

; __device__ __forceinline__ void phase_prep(const Args& a, int l, unsigned char* lds, int G) {
;     const int tid = otid(), lane = tid & 63, wave = tid >> 6;
;     unsigned char* ws = a.ws;
;     const int gw = blockIdx.x * 8 + wave, NGW = G * 8;
;     unsigned* scr = (unsigned*)(lds + wave * 16384);
;     const float* f1n = a.in[I_F1N] + (size_t)l * DM; const float* f2n = a.in[I_F2N] + (size_t)l * DM; const float* mxn = a.in[I_MIXN] + (size_t)l * DM;
;     const float* f1g = a.in[I_F1G] + (size_t)l * DM * FF; const float* f1u = a.in[I_F1U] + (size_t)l * DM * FF; const float* f1d = a.in[I_F1D] + (size_t)l * FF * DM;
;     const float* f2g = a.in[I_F2G] + (size_t)l * DM * FF; const float* f2u = a.in[I_F2U] + (size_t)l * DM * FF; const float* f2d = a.in[I_F2D] + (size_t)l * FF * DM;
;     const float* win = a.in[I_WIN] + (size_t)l * DM * INW; const float* wbr = a.in[I_WBR] + (size_t)l * DM * DM; const float* wout = a.in[I_WOUT] + (size_t)l * DM * DM;
;     const float* wglu = a.in[I_WGLU] + (size_t)l * 512 * 512;
;     constexpr int IT_FU = (DM / 64) * (FF / 64), IT_FD = (FF / 64) * (DM / 64), IT_WA = (DM / 64) * (3584 / 64), IT_WB = (DM / 64) * (6656 / 64),
;                   IT_BR = (1536 / 64) * (DM / 64), IT_WO = (DM / 64) * (DM / 64), IT_GL = (512 / 64) * (512 / 64);
;     constexpr int IT_TOTAL = 4 * IT_FU + 2 * IT_FD + IT_WA + IT_WB + IT_BR + IT_WO + IT_GL;
;     for (int it = gw; it < IT_TOTAL; it += NGW) {
;         int r = it;
;         if (tr_try(r, f1g, FF, DM, FF, 0, f1n, (bf16_t*)(ws + WS_W1U), DM, 0, 1, scr, lane)) continue;
;         if (tr_try(r, f1u, FF, DM, FF, 0, f1n, (bf16_t*)(ws + WS_W1U), DM, 128, 1, scr, lane)) continue;
;         if (tr_try(r, f2g, FF, DM, FF, 0, f2n, (bf16_t*)(ws + WS_W2U), DM, 0, 1, scr, lane)) continue;
;         if (tr_try(r, f2u, FF, DM, FF, 0, f2n, (bf16_t*)(ws + WS_W2U), DM, 128, 1, scr, lane)) continue;
;         if (tr_try(r, f1d, DM, FF, DM, 0, nullptr, (bf16_t*)(ws + WS_W1D), FF, 0, 0, scr, lane)) continue;
;         if (tr_try(r, f2d, DM, FF, DM, 0, nullptr, (bf16_t*)(ws + WS_W2D), FF, 0, 0, scr, lane)) continue;
;         if (tr_try(r, win, INW, DM, 3584, 0, mxn, (bf16_t*)(ws + WS_WIN), DM, 0, 0, scr, lane)) continue;
;         if (tr_try(r, win, INW, DM, 6656, 3600, mxn, (bf16_t*)(ws + WS_WIN), DM, 3584, 0, scr, lane)) continue;
.LBB0_752:
	v_readlane_b32 s0, v248, 24
	v_readlane_b32 s1, v248, 25
	s_andn2_b64 vcc, exec, s[0:1]
	s_cbranch_vccnz .LBB0_1070
	s_cmp_lg_u32 s67, 0
	s_cbranch_scc1 .LBB0_1070
	v_mov_b32_e32 v64, v174
	v_readlane_b32 s0, v254, 39
	s_mov_b64 s[30:31], s[58:59]
	v_readlane_b32 s1, v254, 40
	v_ashrrev_i32_e32 v67, 6, v64
	s_ashr_i32 s87, s86, 31
	v_readlane_b32 s44, v254, 41
	v_add_u32_e32 v66, s0, v67
	s_lshl_b64 s[78:79], s[86:87], 11
	s_lshl_b64 s[0:1], s[86:87], 13
	v_readlane_b32 s54, v254, 51
	v_readlane_b32 s55, v254, 52
	s_add_u32 s66, s54, s0
	v_readlane_b32 s56, v254, 53
	s_addc_u32 s67, s55, s1
	s_mul_i32 s1, s86, 0x5020000
	v_readlane_b32 s57, v254, 54
	s_mul_hi_i32 s0, s86, 0x5020000
	s_mov_b64 s[28:29], s[86:87]
	s_add_u32 s86, s56, s1
	v_and_b32_e32 v69, 63, v64
	s_addc_u32 s87, s57, s0
	s_movk_i32 s0, 0x5d40
	s_mov_b32 s18, 0x1ffff
	v_cmp_gt_i32_e32 vcc, s0, v66
	v_lshlrev_b32_e32 v87, 2, v69
	v_readlane_b32 s45, v254, 42
	v_readlane_b32 s46, v254, 43
	v_readlane_b32 s47, v254, 44
	v_readlane_b32 s48, v254, 45
	v_readlane_b32 s49, v254, 46
	v_readlane_b32 s50, v254, 47
	v_readlane_b32 s51, v254, 48
	v_readlane_b32 s52, v254, 49
	v_readlane_b32 s53, v254, 50
	v_readlane_b32 s58, v254, 55
	v_readlane_b32 s59, v254, 56
	s_cmp_eq_u32 s100, 1
	s_cbranch_scc0 .Lov_keep
	s_mov_b64 vcc, 0
.Lov_keep:
	s_and_saveexec_b64 s[76:77], vcc
	s_cbranch_execz .LBB0_1000
	v_readlane_b32 s48, v254, 41
	s_lshl_b64 s[0:1], s[78:79], 2
	v_readlane_b32 s50, v254, 43
	v_readlane_b32 s58, v254, 51
	v_readlane_b32 s49, v254, 42
	v_readlane_b32 s51, v254, 44
	v_readlane_b32 s59, v254, 52
	s_add_u32 s58, s50, s0
	s_addc_u32 s59, s51, s1
	v_readlane_b32 s36, v254, 2
	v_readlane_b32 s50, v254, 16
	v_readlane_b32 s37, v254, 3
	v_readlane_b32 s51, v254, 17
	s_add_u32 s36, s50, s0
	s_mov_b64 s[16:17], s[28:29]
	v_readlane_b32 s52, v254, 45
	s_addc_u32 s37, s51, s1
	s_mul_i32 s1, s16, 0x2c00000
	v_readlane_b32 s53, v254, 46
	s_mul_hi_i32 s0, s16, 0x2c00000
	s_add_u32 s52, s52, s1
	v_readlane_b32 s54, v254, 47
	s_addc_u32 s53, s53, s0
	v_readlane_b32 s55, v254, 48
	s_add_u32 s54, s54, s1
	v_readlane_b32 s56, v254, 49
	v_readlane_b32 s40, v254, 6
	s_addc_u32 s55, s55, s0
	v_readlane_b32 s57, v254, 50
	v_readlane_b32 s41, v254, 7
	s_add_u32 s40, s56, s1
	v_and_b32_e32 v68, 60, v87
	v_readlane_b32 s60, v254, 53
	s_addc_u32 s41, s57, s0
	v_readlane_b32 s20, v249, 0
	v_lshl_add_u32 v0, v67, 14, 0
	s_waitcnt lgkmcnt(0)
	v_lshrrev_b32_e32 v1, 4, v69
	v_and_b32_e32 v2, 28, v87
	v_lshlrev_b32_e32 v4, 7, v68
	v_readlane_b32 s61, v254, 54
	v_readlane_b32 s21, v249, 1
	s_add_u32 s60, s20, s1
	v_or_b32_e32 v3, v2, v1
	v_add_u32_e32 v5, v0, v4
	v_readlane_b32 s62, v254, 55
	v_readlane_b32 s22, v249, 2
	s_addc_u32 s61, s21, s0
	v_lshl_add_u32 v89, v3, 2, v5
	v_bitop3_b32 v3, v2, 4, v1 bitop3:0x36
	v_readlane_b32 s63, v254, 56
	v_readlane_b32 s23, v249, 3
	s_add_u32 s62, s22, s1
	v_lshlrev_b32_e32 v3, 2, v3
	v_readlane_b32 s42, v254, 8
	v_readlane_b32 s24, v249, 4
	s_addc_u32 s63, s23, s0
	v_add3_u32 v98, v0, v3, v4
	v_add_u32_e32 v99, v5, v3
	v_bitop3_b32 v3, v2, 8, v1 bitop3:0x36
	v_readlane_b32 s43, v254, 9
	v_readlane_b32 s25, v249, 5
	s_add_u32 s42, s24, s1
	v_lshlrev_b32_e32 v3, 2, v3
	v_readlane_b32 s46, v254, 12
	s_addc_u32 s43, s25, s0
	s_lshl_b64 s[0:1], s[28:29], 24
	v_add3_u32 v100, v0, v3, v4
	v_add_u32_e32 v101, v5, v3
	v_bitop3_b32 v3, v2, 12, v1 bitop3:0x36
	v_readlane_b32 s47, v254, 13
	s_add_u32 s4, s46, s0
	v_lshlrev_b32_e32 v3, 2, v3
	v_readlane_b32 s48, v254, 14
	s_addc_u32 s20, s47, s1
	v_add3_u32 v102, v0, v3, v4
	v_add_u32_e32 v103, v5, v3
	v_bitop3_b32 v3, v2, 16, v1 bitop3:0x36
	v_readlane_b32 s49, v254, 15
	s_add_u32 s46, s48, s0
	v_lshlrev_b32_e32 v3, 2, v3
	v_readlane_b32 s44, v254, 10
	s_addc_u32 s47, s49, s1
	s_lshl_b64 s[0:1], s[28:29], 20
	v_lshlrev_b32_e32 v65, 1, v1
	v_add3_u32 v104, v0, v3, v4
	v_add_u32_e32 v105, v5, v3
	v_bitop3_b32 v3, v2, 20, v1 bitop3:0x36
	v_bitop3_b32 v2, v2, 24, v1 bitop3:0x36
	v_bitop3_b32 v1, v87, 28, v1 bitop3:0x26
	v_readlane_b32 s45, v254, 11
	s_add_u32 s16, s44, s0
	v_lshlrev_b32_e32 v1, 2, v1
	s_addc_u32 s17, s45, s1
	v_add3_u32 v110, v0, v1, v4
	v_add_u32_e32 v111, v5, v1
	v_lshlrev_b32_e32 v1, 4, v69
	v_readlane_b32 s0, v251, 61
	v_and_b32_e32 v136, 0x70, v1
	v_readlane_b32 s1, v251, 62
	v_lshlrev_b32_e32 v2, 2, v2
	v_lshrrev_b32_e32 v112, 3, v69
	v_lshl_add_u64 v[70:71], s[0:1], 0, v[136:137]
	v_readlane_b32 s0, v252, 1
	v_readlane_b32 s1, v252, 2
	v_lshlrev_b32_e32 v3, 2, v3
	v_add3_u32 v108, v0, v2, v4
	v_add_u32_e32 v109, v5, v2
	v_bitop3_b32 v2, v112, 28, v87 bitop3:0x48
	v_or_b32_e32 v114, 8, v112
	v_lshl_add_u64 v[72:73], s[0:1], 0, v[136:137]
	v_readlane_b32 s0, v252, 5
	v_add3_u32 v106, v0, v3, v4
	v_add_u32_e32 v107, v5, v3
	v_lshlrev_b32_e32 v1, 7, v112
	v_lshlrev_b32_e32 v2, 2, v2
	v_bitop3_b32 v3, v114, 28, v87 bitop3:0x48
	v_readlane_b32 s1, v252, 6
	v_add3_u32 v113, v0, v1, v2
	v_lshlrev_b32_e32 v1, 7, v114
	v_lshlrev_b32_e32 v3, 2, v3
	v_or_b32_e32 v116, 16, v112
	v_lshl_add_u64 v[74:75], s[0:1], 0, v[136:137]
	v_readlane_b32 s0, v252, 7
	v_add3_u32 v115, v0, v1, v3
	v_bitop3_b32 v3, v116, 28, v87 bitop3:0x48
	v_readlane_b32 s1, v252, 8
	v_lshlrev_b32_e32 v1, 7, v116
	v_lshlrev_b32_e32 v3, 2, v3
	v_or_b32_e32 v118, 24, v112
	v_lshl_add_u64 v[76:77], s[0:1], 0, v[136:137]
	v_readlane_b32 s0, v253, 19
	v_add3_u32 v117, v0, v1, v3
	v_bitop3_b32 v3, v118, 28, v87 bitop3:0x48
	v_readlane_b32 s1, v253, 20
	v_lshlrev_b32_e32 v1, 7, v118
	v_lshlrev_b32_e32 v3, 2, v3
	v_or_b32_e32 v120, 32, v112
	v_lshl_add_u64 v[78:79], s[0:1], 0, v[136:137]
	v_readlane_b32 s0, v252, 11
	v_add3_u32 v119, v0, v1, v3
	v_lshlrev_b32_e32 v1, 7, v120
	v_or_b32_e32 v122, 40, v112
	v_readlane_b32 s1, v252, 12
	v_add3_u32 v121, v0, v1, v2
	v_bitop3_b32 v2, v122, 28, v87 bitop3:0x48
	v_lshl_add_u64 v[80:81], s[0:1], 0, v[136:137]
	v_readlane_b32 s0, v252, 57
	v_lshlrev_b32_e32 v1, 7, v122
	v_lshlrev_b32_e32 v2, 2, v2
	v_or_b32_e32 v124, 48, v112
	v_readlane_b32 s1, v252, 58
	v_add3_u32 v123, v0, v1, v2
	v_bitop3_b32 v2, v124, 28, v87 bitop3:0x48
	v_lshl_add_u64 v[82:83], s[0:1], 0, v[136:137]
	v_readlane_b32 s0, v252, 35
	v_lshlrev_b32_e32 v1, 7, v124
	v_lshlrev_b32_e32 v2, 2, v2
	v_or_b32_e32 v126, 56, v112
	v_readlane_b32 s1, v252, 36
	v_add3_u32 v125, v0, v1, v2
	v_bitop3_b32 v2, v126, 28, v87 bitop3:0x48
	v_lshl_add_u64 v[84:85], s[0:1], 0, v[136:137]
	v_readlane_b32 s0, v254, 59
	v_readlane_b32 s26, v249, 6
	v_readlane_b32 s24, v251, 63
	v_lshlrev_b32_e32 v1, 7, v126
	v_lshlrev_b32_e32 v2, 2, v2
	s_add_u32 s44, s4, 0x400000
	v_lshl_add_u32 v86, v67, 6, s0
	v_readlane_b32 s0, v254, 0
	s_mov_b32 s26, 0x1e801000
	v_readlane_b32 s25, v252, 0
	v_add3_u32 v127, v0, v1, v2
	s_addc_u32 s45, s20, 0
	v_lshl_add_u32 v88, v67, 7, s0
	s_mov_b64 s[64:65], 0
	v_mov_b32_e32 v128, v66
	v_readlane_b32 s38, v254, 4
	v_readlane_b32 s39, v254, 5
	v_readlane_b32 s27, v249, 7
	s_branch .LBB0_757

; __device__ __forceinline__ unsigned f2bf(float f) { return pk2(f, 0.f) & 0xffffu; }
; __device__ __forceinline__ void phase_prep(const Args& a, int l, unsigned char* lds, int G) {
;     ...
;     {
;         const float* pw = a.in[I_POOLW] + (size_t)l * 4 * 128 * 128; const float* ps = a.in[I_POOLS] + (size_t)l * 512;
;         bf16_t* WbT = (bf16_t*)(ws + WS_WBR);
;         const int n0 = blockIdx.x * 8, k = tid, g = k >> 7;
;         const float* pr = pw + (size_t)k * 128;
;         float s[8];
; #pragma unroll
;         for (int i = 0; i < 8; ++i) s[i] = 0.f;
; #pragma unroll 4
;         for (int d = 0; d < 128; ++d) {
;             const float pv = pr[d] * ps[g * 128 + d];
;             const f32x4 w0 = *(const f32x4*)(wbr + (size_t)(g * 128 + d) * DM + n0), w1 = *(const f32x4*)(wbr + (size_t)(g * 128 + d) * DM + n0 + 4);
;             s[0] += pv * w0[0]; s[1] += pv * w0[1]; s[2] += pv * w0[2]; s[3] += pv * w0[3]; s[4] += pv * w1[0]; s[5] += pv * w1[1]; s[6] += pv * w1[2]; s[7] += pv * w1[3];
;         }
; #pragma unroll
;         for (int i = 0; i < 8; ++i) WbT[(size_t)(n0 + i) * DM + k] = (bf16_t)f2bf(s[i]);
.LBB0_1000:
	s_or_b64 exec, exec, s[76:77]
	s_cmp_eq_u32 s100, 2
	s_cbranch_scc0 .Lov_cont
	v_readlane_b32 s0, v246, 0
	v_readlane_b32 s1, v246, 1
	v_readlane_b32 s2, v246, 2
	v_readlane_b32 s3, v246, 3
	v_readlane_b32 s4, v246, 4
	v_readlane_b32 s5, v246, 5
	v_readlane_b32 s6, v246, 6
	v_readlane_b32 s7, v246, 7
	v_readlane_b32 s8, v246, 8
	v_readlane_b32 s9, v246, 9
	v_readlane_b32 s10, v246, 10
	v_readlane_b32 s11, v246, 11
	v_readlane_b32 s12, v246, 12
	v_readlane_b32 s13, v246, 13
	v_readlane_b32 s14, v246, 14
	v_readlane_b32 s15, v246, 15
	v_readlane_b32 s16, v246, 16
	v_readlane_b32 s17, v246, 17
	v_readlane_b32 s18, v246, 18
	v_readlane_b32 s19, v246, 19
	v_readlane_b32 s20, v246, 20
	v_readlane_b32 s21, v246, 21
	v_readlane_b32 s22, v246, 22
	v_readlane_b32 s23, v246, 23
	v_readlane_b32 s24, v246, 24
	v_readlane_b32 s25, v246, 25
	v_readlane_b32 s26, v246, 26
	v_readlane_b32 s27, v246, 27
	v_readlane_b32 s28, v246, 28
	v_readlane_b32 s29, v246, 29
	v_readlane_b32 s30, v246, 30
	v_readlane_b32 s31, v246, 31
	v_readlane_b32 s32, v246, 32
	v_readlane_b32 s33, v246, 33
	v_readlane_b32 s34, v246, 34
	v_readlane_b32 s35, v246, 35
	v_readlane_b32 s36, v246, 36
	v_readlane_b32 s37, v246, 37
	v_readlane_b32 s38, v246, 38
	v_readlane_b32 s39, v246, 39
	v_readlane_b32 s40, v246, 40
	v_readlane_b32 s41, v246, 41
	v_readlane_b32 s42, v246, 42
	v_readlane_b32 s43, v246, 43
	v_readlane_b32 s44, v246, 44
	v_readlane_b32 s45, v246, 45
	v_readlane_b32 s46, v246, 46
	v_readlane_b32 s47, v246, 47
	v_readlane_b32 s48, v246, 48
	v_readlane_b32 s49, v246, 49
	v_readlane_b32 s50, v246, 50
	v_readlane_b32 s51, v246, 51
	v_readlane_b32 s52, v246, 52
	v_readlane_b32 s53, v246, 53
	v_readlane_b32 s54, v246, 54
	v_readlane_b32 s55, v246, 55
	v_readlane_b32 s56, v246, 56
	v_readlane_b32 s57, v246, 57
	v_readlane_b32 s58, v246, 58
	v_readlane_b32 s59, v246, 59
	v_readlane_b32 s60, v246, 60
	v_readlane_b32 s61, v246, 61
	v_readlane_b32 s62, v246, 62
	v_readlane_b32 s63, v246, 63
	v_readlane_b32 s64, v247, 0
	v_readlane_b32 s65, v247, 1
	v_readlane_b32 s66, v247, 2
	v_readlane_b32 s67, v247, 3
	v_readlane_b32 s68, v247, 4
	v_readlane_b32 s69, v247, 5
	v_readlane_b32 s70, v247, 6
	v_readlane_b32 s71, v247, 7
	v_readlane_b32 s72, v247, 8
	v_readlane_b32 s73, v247, 9
	v_readlane_b32 s74, v247, 10
	v_readlane_b32 s75, v247, 11
	v_readlane_b32 s76, v247, 12
	v_readlane_b32 s77, v247, 13
	v_readlane_b32 s78, v247, 14
	v_readlane_b32 s79, v247, 15
	v_readlane_b32 s80, v247, 16
	v_readlane_b32 s81, v247, 17
	v_readlane_b32 s82, v247, 18
	v_readlane_b32 s83, v247, 19
	v_readlane_b32 s84, v247, 20
	v_readlane_b32 s85, v247, 21
	v_readlane_b32 s86, v247, 22
	v_readlane_b32 s87, v247, 23
	v_readlane_b32 s88, v247, 24
	v_readlane_b32 s89, v247, 25
	v_readlane_b32 s90, v247, 26
	v_readlane_b32 s91, v247, 27
	v_readlane_b32 s92, v247, 28
	v_readlane_b32 s93, v247, 29
	v_readlane_b32 s94, v247, 30
	v_readlane_b32 s95, v247, 31
	v_readlane_b32 s96, v247, 32
	v_readlane_b32 s97, v247, 33
	v_readlane_b32 s98, v247, 34
	v_readlane_b32 s99, v247, 35
	s_nop 4
	s_mov_b32 s100, 0
	s_branch .LBB0_1070
.Lov_cont:
	s_lshl_b64 s[0:1], s[28:29], 18
	s_lshl_b64 s[22:23], s[28:29], 24
	v_readlane_b32 s4, v254, 1
	s_add_u32 s22, s4, s22
	v_readlane_b32 s4, v254, 18
	s_addc_u32 s23, s4, s23
	v_readlane_b32 s4, v254, 19
	v_ashrrev_i32_e32 v65, 31, v64
	s_add_u32 s0, s4, s0
	v_readlane_b32 s4, v254, 20
	s_waitcnt lgkmcnt(0)
	v_lshlrev_b64 v[0:1], 9, v[64:65]
	s_addc_u32 s1, s4, s1
	v_and_b32_e32 v6, 0xffffff80, v64
	v_lshl_add_u64 v[4:5], s[0:1], 0, v[0:1]
	v_readlane_b32 s0, v254, 21
	v_ashrrev_i32_e32 v7, 31, v6
	s_add_u32 s0, s0, s78
	v_readlane_b32 s1, v254, 38
	v_readlane_b32 s20, v251, 57
	v_lshlrev_b64 v[2:3], 13, v[6:7]
	s_addc_u32 s1, s1, s79
	v_mov_b32_e32 v0, 0
	v_readlane_b32 s72, v248, 22
	v_readlane_b32 s21, v251, 58
	v_lshl_add_u64 v[2:3], s[22:23], 0, v[2:3]
	v_lshl_add_u64 v[8:9], v[6:7], 2, s[0:1]
	s_mov_b64 s[0:1], 0
	v_mov_b32_e32 v1, v0
	v_mov_b32_e32 v12, v0
	v_mov_b32_e32 v13, v0
	v_mov_b32_e32 v10, v0
	v_mov_b32_e32 v11, v0
	v_mov_b32_e32 v6, v0
	v_mov_b32_e32 v7, v0
	v_readlane_b32 s73, v248, 23
	s_mov_b64 s[58:59], s[30:31]
	s_movk_i32 s8, 0x2000
	s_movk_i32 s16, 0x4000
	s_movk_i32 s17, 0x3000
	s_mov_b32 s19, 0xa040
	s_mov_b64 s[24:25], 0x4000

; __global__ void __launch_bounds__(512, 2) mega_fwd(Args a) {
;     ...
;         if (k == 0) {
;     ...
;             phase_prep(a, l, lds, G);
.LBB0_1070:
	s_cmp_eq_u32 s100, 1
	s_cbranch_scc0 .Lov_exit
	v_writelane_b32 v246, s0, 0
	v_writelane_b32 v246, s1, 1
	v_writelane_b32 v246, s2, 2
	v_writelane_b32 v246, s3, 3
	v_writelane_b32 v246, s4, 4
	v_writelane_b32 v246, s5, 5
	v_writelane_b32 v246, s6, 6
	v_writelane_b32 v246, s7, 7
	v_writelane_b32 v246, s8, 8
	v_writelane_b32 v246, s9, 9
	v_writelane_b32 v246, s10, 10
	v_writelane_b32 v246, s11, 11
	v_writelane_b32 v246, s12, 12
	v_writelane_b32 v246, s13, 13
	v_writelane_b32 v246, s14, 14
	v_writelane_b32 v246, s15, 15
	v_writelane_b32 v246, s16, 16
	v_writelane_b32 v246, s17, 17
	v_writelane_b32 v246, s18, 18
	v_writelane_b32 v246, s19, 19
	v_writelane_b32 v246, s20, 20
	v_writelane_b32 v246, s21, 21
	v_writelane_b32 v246, s22, 22
	v_writelane_b32 v246, s23, 23
	v_writelane_b32 v246, s24, 24
	v_writelane_b32 v246, s25, 25
	v_writelane_b32 v246, s26, 26
	v_writelane_b32 v246, s27, 27
	v_writelane_b32 v246, s28, 28
	v_writelane_b32 v246, s29, 29
	v_writelane_b32 v246, s30, 30
	v_writelane_b32 v246, s31, 31
	v_writelane_b32 v246, s32, 32
	v_writelane_b32 v246, s33, 33
	v_writelane_b32 v246, s34, 34
	v_writelane_b32 v246, s35, 35
	v_writelane_b32 v246, s36, 36
	v_writelane_b32 v246, s37, 37
	v_writelane_b32 v246, s38, 38
	v_writelane_b32 v246, s39, 39
	v_writelane_b32 v246, s40, 40
	v_writelane_b32 v246, s41, 41
	v_writelane_b32 v246, s42, 42
	v_writelane_b32 v246, s43, 43
	v_writelane_b32 v246, s44, 44
	v_writelane_b32 v246, s45, 45
	v_writelane_b32 v246, s46, 46
	v_writelane_b32 v246, s47, 47
	v_writelane_b32 v246, s48, 48
	v_writelane_b32 v246, s49, 49
	v_writelane_b32 v246, s50, 50
	v_writelane_b32 v246, s51, 51
	v_writelane_b32 v246, s52, 52
	v_writelane_b32 v246, s53, 53
	v_writelane_b32 v246, s54, 54
	v_writelane_b32 v246, s55, 55
	v_writelane_b32 v246, s56, 56
	v_writelane_b32 v246, s57, 57
	v_writelane_b32 v246, s58, 58
	v_writelane_b32 v246, s59, 59
	v_writelane_b32 v246, s60, 60
	v_writelane_b32 v246, s61, 61
	v_writelane_b32 v246, s62, 62
	v_writelane_b32 v246, s63, 63
	v_writelane_b32 v247, s64, 0
	v_writelane_b32 v247, s65, 1
	v_writelane_b32 v247, s66, 2
	v_writelane_b32 v247, s67, 3
	v_writelane_b32 v247, s68, 4
	v_writelane_b32 v247, s69, 5
	v_writelane_b32 v247, s70, 6
	v_writelane_b32 v247, s71, 7
	v_writelane_b32 v247, s72, 8
	v_writelane_b32 v247, s73, 9
	v_writelane_b32 v247, s74, 10
	v_writelane_b32 v247, s75, 11
	v_writelane_b32 v247, s76, 12
	v_writelane_b32 v247, s77, 13
	v_writelane_b32 v247, s78, 14
	v_writelane_b32 v247, s79, 15
	v_writelane_b32 v247, s80, 16
	v_writelane_b32 v247, s81, 17
	v_writelane_b32 v247, s82, 18
	v_writelane_b32 v247, s83, 19
	v_writelane_b32 v247, s84, 20
	v_writelane_b32 v247, s85, 21
	v_writelane_b32 v247, s86, 22
	v_writelane_b32 v247, s87, 23
	v_writelane_b32 v247, s88, 24
	v_writelane_b32 v247, s89, 25
	v_writelane_b32 v247, s90, 26
	v_writelane_b32 v247, s91, 27
	v_writelane_b32 v247, s92, 28
	v_writelane_b32 v247, s93, 29
	v_writelane_b32 v247, s94, 30
	v_writelane_b32 v247, s95, 31
	v_writelane_b32 v247, s96, 32
	v_writelane_b32 v247, s97, 33
	v_writelane_b32 v247, s98, 34
	v_writelane_b32 v247, s99, 35
	s_mov_b32 s100, 2
	s_branch .Lov_tramp
